# w_o GEMM epilogues: the 16 residual loads of a tile issued during the first k-step (cross-loop prefetch) instead of at epilogue start; bit-identical
# speedup vs baseline: 1.0075x; 1.0075x over previous
.LBB0_252:
	s_lshl_b32 s94, s14, 7
	s_ashr_i32 s95, s94, 31
	s_lshl_b32 s96, s15, 7
	s_lshl_b64 s[14:15], s[94:95], 11
	s_add_u32 s28, s36, s14
	s_addc_u32 s29, s37, s15
	s_ashr_i32 s97, s96, 31
	s_lshl_b64 s[14:15], s[96:97], 11
	v_readlane_b32 s52, v245, 37
	v_readlane_b32 s53, v245, 38
	s_add_u32 s14, s52, s14
	s_addc_u32 s15, s53, s15
	v_readfirstlane_b32 s68, v88
	v_mov_b32_e32 v2, s15
	v_mov_b32_e32 v3, s29
	v_mov_b32_e32 v4, s14
	v_mov_b32_e32 v5, s28
	s_add_u32 s98, s28, 0x80
	s_addc_u32 s99, s29, 0
	v_lshl_add_u64 v[72:73], s[28:29], 0, v[64:65]
	s_mov_b32 m0, s68
	v_cndmask_b32_e64 v1, v2, v3, s[4:5]
	v_cndmask_b32_e64 v0, v4, v5, s[4:5]
	v_readfirstlane_b32 s69, v91
	global_load_lds_dwordx4 v[72:73], off
	v_lshl_add_u64 v[74:75], v[0:1], 0, v[66:67]
	s_mov_b32 m0, s69
	v_cndmask_b32_e64 v1, v2, v3, s[6:7]
	v_cndmask_b32_e64 v0, v4, v5, s[6:7]
	v_readfirstlane_b32 s70, v92
	global_load_lds_dwordx4 v[74:75], off
	v_lshl_add_u64 v[76:77], v[0:1], 0, v[68:69]
	s_mov_b32 m0, s70
	v_cndmask_b32_e64 v1, v2, v3, s[8:9]
	v_cndmask_b32_e64 v0, v4, v5, s[8:9]
	v_readfirstlane_b32 s71, v93
	global_load_lds_dwordx4 v[76:77], off
	v_lshl_add_u64 v[78:79], v[0:1], 0, v[70:71]
	s_mov_b32 m0, s71
	v_readfirstlane_b32 s29, v94
	global_load_lds_dwordx4 v[78:79], off
	s_add_u32 s100, s14, 0x80
	s_addc_u32 s101, s15, 0
	v_lshl_add_u64 v[80:81], s[14:15], 0, v[64:65]
	s_mov_b32 m0, s29
	v_readfirstlane_b32 s85, v95
	global_load_lds_dwordx4 v[80:81], off
	v_lshl_add_u64 v[82:83], s[14:15], 0, v[66:67]
	s_mov_b32 m0, s85
	v_readfirstlane_b32 s86, v96
	global_load_lds_dwordx4 v[82:83], off
	v_lshl_add_u64 v[84:85], s[14:15], 0, v[68:69]
	s_mov_b32 m0, s86
	v_readfirstlane_b32 s87, v97
	global_load_lds_dwordx4 v[84:85], off
	v_lshl_add_u64 v[86:87], s[14:15], 0, v[70:71]
	s_mov_b32 m0, s87
	v_readfirstlane_b32 s14, v98
	global_load_lds_dwordx4 v[86:87], off
	s_mov_b32 m0, s14
	v_readfirstlane_b32 s15, v99
	s_waitcnt vmcnt(0)
	s_waitcnt vmcnt(0) lgkmcnt(0)
	s_barrier
	global_load_lds_dwordx4 v64, s[98:99]
	s_mov_b32 m0, s15
	v_readfirstlane_b32 s72, v100
	global_load_lds_dwordx4 v66, s[98:99]
	s_mov_b32 m0, s72
	v_readfirstlane_b32 s73, v101
	global_load_lds_dwordx4 v68, s[98:99]
	s_mov_b32 m0, s73
	v_readfirstlane_b32 s95, v102
	global_load_lds_dwordx4 v70, s[98:99]
	s_mov_b32 m0, s95
	v_readfirstlane_b32 s97, v103
	global_load_lds_dwordx4 v64, s[100:101]
	s_mov_b32 m0, s97
	v_readfirstlane_b32 s28, v104
	global_load_lds_dwordx4 v66, s[100:101]
	s_mov_b32 m0, s28
	v_readfirstlane_b32 s84, v105
	global_load_lds_dwordx4 v68, s[100:101]
	s_mov_b32 m0, s84
	v_readfirstlane_b32 s34, v94
	global_load_lds_dwordx4 v70, s[100:101]
	s_add_u32 s98, s98, 0x80
	s_addc_u32 s99, s99, 0
	s_add_u32 s100, s100, 0x80
	s_addc_u32 s101, s101, 0
	ds_read_b128 v[0:3], v106
	ds_read_b128 v[4:7], v107 offset:16384
	ds_read_b128 v[8:11], v106 offset:4096
	ds_read_b128 v[12:15], v107 offset:20480
	s_waitcnt lgkmcnt(0)
	v_mfma_f32_32x32x16_bf16 v[48:63], v[4:7], v[0:3], 0
	ds_read_b128 v[114:117], v108
	ds_read_b128 v[118:121], v109 offset:16384
	ds_read_b128 v[122:125], v108 offset:4096
	ds_read_b128 v[126:129], v109 offset:20480
	s_mov_b32 m0, s68
	v_readfirstlane_b32 s35, v95
	v_readlane_b32 s54, v245, 39
	v_readlane_b32 s55, v245, 40
	v_readlane_b32 s56, v245, 41
	v_readlane_b32 s57, v245, 42
	v_mfma_f32_32x32x16_bf16 v[32:47], v[12:15], v[0:3], 0
	v_readlane_b32 s58, v245, 43
	v_readlane_b32 s59, v245, 44
	v_readlane_b32 s60, v245, 45
	v_readlane_b32 s61, v245, 46
	v_readlane_b32 s62, v245, 47
	v_readlane_b32 s63, v245, 48
	v_readlane_b32 s64, v245, 49
	v_mfma_f32_32x32x16_bf16 v[16:31], v[4:7], v[8:11], 0
	v_readlane_b32 s65, v245, 50
	v_readlane_b32 s66, v245, 51
	v_readlane_b32 s67, v245, 52
	v_readlane_b32 s52, v245, 5
	v_readlane_b32 s53, v245, 6
	v_add_u32_e32 v236, s94, v89
	v_or_b32_e32 v240, s96, v90
	v_ashrrev_i32_e32 v237, 31, v236
	v_ashrrev_i32_e32 v241, 31, v240
	v_or_b32_e32 v234, 32, v236
	v_lshlrev_b64 v[238:239], 12, v[236:237]
	v_lshlrev_b64 v[240:241], 2, v[240:241]
	v_ashrrev_i32_e32 v235, 31, v234
	v_lshlrev_b64 v[234:235], 12, v[234:235]
	v_lshl_add_u64 v[242:243], s[52:53], 0, v[238:239]
	v_lshl_add_u64 v[230:231], s[52:53], 0, v[234:235]
	v_lshl_add_u64 v[242:243], v[242:243], 0, v[240:241]
	v_lshl_add_u64 v[230:231], v[230:231], 0, v[240:241]
	global_load_dwordx4 v[164:167], v[242:243], off
	global_load_dwordx4 v[168:171], v[242:243], off offset:32
	global_load_dwordx4 v[172:175], v[242:243], off offset:64
	global_load_dwordx4 v[176:179], v[242:243], off offset:96
	global_load_dwordx4 v[180:183], v[242:243], off offset:128
	global_load_dwordx4 v[184:187], v[242:243], off offset:160
	global_load_dwordx4 v[188:191], v[242:243], off offset:192
	global_load_dwordx4 v[192:195], v[242:243], off offset:224
	global_load_dwordx4 v[196:199], v[230:231], off
	global_load_dwordx4 v[200:203], v[230:231], off offset:32
	global_load_dwordx4 v[204:207], v[230:231], off offset:64
	global_load_dwordx4 v[208:211], v[230:231], off offset:96
	global_load_dwordx4 v[212:215], v[230:231], off offset:128
	global_load_dwordx4 v[216:219], v[230:231], off offset:160
	global_load_dwordx4 v[220:223], v[230:231], off offset:192
	global_load_dwordx4 v[224:227], v[230:231], off offset:224
	s_add_i32 s13, s13, s33
	v_readlane_b32 s54, v245, 7
	v_mfma_f32_32x32x16_bf16 v[0:15], v[12:15], v[8:11], 0
	v_readlane_b32 s55, v245, 8
	v_readlane_b32 s56, v245, 9
	v_readlane_b32 s57, v245, 10
	v_readlane_b32 s58, v245, 11
	v_readlane_b32 s59, v245, 12
	v_readlane_b32 s60, v245, 13
	v_readlane_b32 s61, v245, 14
	s_waitcnt lgkmcnt(0)
	v_mfma_f32_32x32x16_bf16 v[48:63], v[118:121], v[114:117], v[48:63]
	v_readlane_b32 s62, v245, 15
	v_readlane_b32 s63, v245, 16
	v_readlane_b32 s64, v245, 17
	v_readlane_b32 s65, v245, 18
	v_readlane_b32 s66, v245, 19
	v_readlane_b32 s67, v245, 20
	v_mfma_f32_32x32x16_bf16 v[32:47], v[126:129], v[114:117], v[32:47]
	v_mfma_f32_32x32x16_bf16 v[16:31], v[118:121], v[122:125], v[16:31]
	v_mfma_f32_32x32x16_bf16 v[0:15], v[126:129], v[122:125], v[0:15]
	ds_read_b128 v[114:117], v110
	ds_read_b128 v[118:121], v111 offset:16384
	ds_read_b128 v[122:125], v110 offset:4096
	ds_read_b128 v[126:129], v111 offset:20480
	s_waitcnt lgkmcnt(0)
	v_mfma_f32_32x32x16_bf16 v[48:63], v[118:121], v[114:117], v[48:63]
	v_mfma_f32_32x32x16_bf16 v[32:47], v[126:129], v[114:117], v[32:47]
	v_mfma_f32_32x32x16_bf16 v[16:31], v[118:121], v[122:125], v[16:31]
	v_mfma_f32_32x32x16_bf16 v[0:15], v[126:129], v[122:125], v[0:15]
	ds_read_b128 v[114:117], v112
	ds_read_b128 v[118:121], v113 offset:16384
	ds_read_b128 v[122:125], v112 offset:4096
	ds_read_b128 v[126:129], v113 offset:20480
	s_waitcnt vmcnt(0)
	s_waitcnt vmcnt(0) lgkmcnt(0)
	s_barrier
	v_mfma_f32_32x32x16_bf16 v[48:63], v[118:121], v[114:117], v[48:63]
	v_mfma_f32_32x32x16_bf16 v[32:47], v[126:129], v[114:117], v[32:47]
	global_load_lds_dwordx4 v64, s[98:99]
	s_mov_b32 m0, s69
	s_nop 0
	global_load_lds_dwordx4 v66, s[98:99]
	s_mov_b32 m0, s70
	v_mfma_f32_32x32x16_bf16 v[16:31], v[118:121], v[122:125], v[16:31]
	global_load_lds_dwordx4 v68, s[98:99]
	s_mov_b32 m0, s71
	s_nop 0
	global_load_lds_dwordx4 v70, s[98:99]
	s_mov_b32 m0, s29
	v_mfma_f32_32x32x16_bf16 v[0:15], v[126:129], v[122:125], v[0:15]
	global_load_lds_dwordx4 v64, s[100:101]
	s_mov_b32 m0, s85
	s_nop 0
	global_load_lds_dwordx4 v66, s[100:101]
	s_mov_b32 m0, s86
	s_nop 0
	global_load_lds_dwordx4 v68, s[100:101]
	s_mov_b32 m0, s87
	s_nop 0
	global_load_lds_dwordx4 v70, s[100:101]
	s_add_u32 s98, s98, 0x80
	s_addc_u32 s99, s99, 0
	s_add_u32 s100, s100, 0x80
	s_addc_u32 s101, s101, 0
	ds_read_b128 v[114:117], v106 offset:32768
	ds_read_b128 v[118:121], v107 offset:49152
	ds_read_b128 v[122:125], v106 offset:36864
	ds_read_b128 v[126:129], v107 offset:53248
	s_waitcnt lgkmcnt(0)
	v_mfma_f32_32x32x16_bf16 v[48:63], v[118:121], v[114:117], v[48:63]
	s_mov_b32 m0, s14
	v_mfma_f32_32x32x16_bf16 v[32:47], v[126:129], v[114:117], v[32:47]
	v_mfma_f32_32x32x16_bf16 v[16:31], v[118:121], v[122:125], v[16:31]
	v_mfma_f32_32x32x16_bf16 v[0:15], v[126:129], v[122:125], v[0:15]
	ds_read_b128 v[114:117], v108 offset:32768
	ds_read_b128 v[118:121], v109 offset:49152
	ds_read_b128 v[122:125], v108 offset:36864
	ds_read_b128 v[126:129], v109 offset:53248
	s_waitcnt lgkmcnt(0)
	v_mfma_f32_32x32x16_bf16 v[48:63], v[118:121], v[114:117], v[48:63]
	v_mfma_f32_32x32x16_bf16 v[32:47], v[126:129], v[114:117], v[32:47]
	v_mfma_f32_32x32x16_bf16 v[16:31], v[118:121], v[122:125], v[16:31]
	v_mfma_f32_32x32x16_bf16 v[0:15], v[126:129], v[122:125], v[0:15]
	ds_read_b128 v[114:117], v110 offset:32768
	ds_read_b128 v[118:121], v111 offset:49152
	ds_read_b128 v[122:125], v110 offset:36864
	ds_read_b128 v[126:129], v111 offset:53248
	s_waitcnt lgkmcnt(0)
	v_mfma_f32_32x32x16_bf16 v[48:63], v[118:121], v[114:117], v[48:63]
	v_mfma_f32_32x32x16_bf16 v[32:47], v[126:129], v[114:117], v[32:47]
	v_mfma_f32_32x32x16_bf16 v[16:31], v[118:121], v[122:125], v[16:31]
	v_mfma_f32_32x32x16_bf16 v[0:15], v[126:129], v[122:125], v[0:15]
	ds_read_b128 v[114:117], v112 offset:32768
	ds_read_b128 v[118:121], v113 offset:49152
	ds_read_b128 v[122:125], v112 offset:36864
	ds_read_b128 v[126:129], v113 offset:53248
	s_waitcnt vmcnt(0)
	s_waitcnt vmcnt(0) lgkmcnt(0)
	s_barrier
	v_mfma_f32_32x32x16_bf16 v[48:63], v[118:121], v[114:117], v[48:63]
	v_mfma_f32_32x32x16_bf16 v[32:47], v[126:129], v[114:117], v[32:47]
	global_load_lds_dwordx4 v64, s[98:99]
	s_mov_b32 m0, s15
	s_nop 0
	global_load_lds_dwordx4 v66, s[98:99]
	s_mov_b32 m0, s72
	v_mfma_f32_32x32x16_bf16 v[16:31], v[118:121], v[122:125], v[16:31]
	global_load_lds_dwordx4 v68, s[98:99]
	s_mov_b32 m0, s73
	s_nop 0
	global_load_lds_dwordx4 v70, s[98:99]
	s_mov_b32 m0, s95
	v_mfma_f32_32x32x16_bf16 v[0:15], v[126:129], v[122:125], v[0:15]
	global_load_lds_dwordx4 v64, s[100:101]
	s_mov_b32 m0, s97
	s_nop 0
	global_load_lds_dwordx4 v66, s[100:101]
	s_mov_b32 m0, s28
	s_nop 0
	global_load_lds_dwordx4 v68, s[100:101]
	s_mov_b32 m0, s84
	s_nop 0
	global_load_lds_dwordx4 v70, s[100:101]
	s_add_u32 s98, s98, 0x80
	s_addc_u32 s99, s99, 0
	s_add_u32 s100, s100, 0x80
	s_addc_u32 s101, s101, 0
	ds_read_b128 v[114:117], v106
	ds_read_b128 v[118:121], v107 offset:16384
	ds_read_b128 v[122:125], v106 offset:4096
	ds_read_b128 v[126:129], v107 offset:20480
	s_waitcnt lgkmcnt(0)
	v_mfma_f32_32x32x16_bf16 v[48:63], v[118:121], v[114:117], v[48:63]
	s_mov_b32 m0, s68
	v_mfma_f32_32x32x16_bf16 v[32:47], v[126:129], v[114:117], v[32:47]
	v_mfma_f32_32x32x16_bf16 v[16:31], v[118:121], v[122:125], v[16:31]
	v_mfma_f32_32x32x16_bf16 v[0:15], v[126:129], v[122:125], v[0:15]
	ds_read_b128 v[114:117], v108
	ds_read_b128 v[118:121], v109 offset:16384
	ds_read_b128 v[122:125], v108 offset:4096
	ds_read_b128 v[126:129], v109 offset:20480
	s_waitcnt lgkmcnt(0)
	v_mfma_f32_32x32x16_bf16 v[48:63], v[118:121], v[114:117], v[48:63]
	v_mfma_f32_32x32x16_bf16 v[32:47], v[126:129], v[114:117], v[32:47]
	v_mfma_f32_32x32x16_bf16 v[16:31], v[118:121], v[122:125], v[16:31]
	v_mfma_f32_32x32x16_bf16 v[0:15], v[126:129], v[122:125], v[0:15]
	ds_read_b128 v[114:117], v110
	ds_read_b128 v[118:121], v111 offset:16384
	ds_read_b128 v[122:125], v110 offset:4096
	ds_read_b128 v[126:129], v111 offset:20480
	s_waitcnt lgkmcnt(0)
	v_mfma_f32_32x32x16_bf16 v[48:63], v[118:121], v[114:117], v[48:63]
	v_mfma_f32_32x32x16_bf16 v[32:47], v[126:129], v[114:117], v[32:47]
	v_mfma_f32_32x32x16_bf16 v[16:31], v[118:121], v[122:125], v[16:31]
	v_mfma_f32_32x32x16_bf16 v[0:15], v[126:129], v[122:125], v[0:15]
	ds_read_b128 v[114:117], v112
	ds_read_b128 v[118:121], v113 offset:16384
	ds_read_b128 v[122:125], v112 offset:4096
	ds_read_b128 v[126:129], v113 offset:20480
	s_waitcnt vmcnt(0)
	s_waitcnt vmcnt(0) lgkmcnt(0)
	s_barrier
	v_mfma_f32_32x32x16_bf16 v[48:63], v[118:121], v[114:117], v[48:63]
	v_mfma_f32_32x32x16_bf16 v[32:47], v[126:129], v[114:117], v[32:47]
	global_load_lds_dwordx4 v64, s[98:99]
	s_mov_b32 m0, s69
	s_nop 0
	global_load_lds_dwordx4 v66, s[98:99]
	s_mov_b32 m0, s70
	v_mfma_f32_32x32x16_bf16 v[16:31], v[118:121], v[122:125], v[16:31]
	global_load_lds_dwordx4 v68, s[98:99]
	s_mov_b32 m0, s71
	s_nop 0
	global_load_lds_dwordx4 v70, s[98:99]
	s_mov_b32 m0, s29
	v_mfma_f32_32x32x16_bf16 v[0:15], v[126:129], v[122:125], v[0:15]
	global_load_lds_dwordx4 v64, s[100:101]
	s_mov_b32 m0, s85
	s_nop 0
	global_load_lds_dwordx4 v66, s[100:101]
	s_mov_b32 m0, s86
	s_nop 0
	global_load_lds_dwordx4 v68, s[100:101]
	s_mov_b32 m0, s87
	s_nop 0
	global_load_lds_dwordx4 v70, s[100:101]
	s_add_u32 s98, s98, 0x80
	s_addc_u32 s99, s99, 0
	s_add_u32 s100, s100, 0x80
	s_addc_u32 s101, s101, 0
	ds_read_b128 v[114:117], v106 offset:32768
	ds_read_b128 v[118:121], v107 offset:49152
	ds_read_b128 v[122:125], v106 offset:36864
	ds_read_b128 v[126:129], v107 offset:53248
	s_waitcnt lgkmcnt(0)
	v_mfma_f32_32x32x16_bf16 v[48:63], v[118:121], v[114:117], v[48:63]
	s_mov_b32 m0, s14
	v_mfma_f32_32x32x16_bf16 v[32:47], v[126:129], v[114:117], v[32:47]
	v_mfma_f32_32x32x16_bf16 v[16:31], v[118:121], v[122:125], v[16:31]
	v_mfma_f32_32x32x16_bf16 v[0:15], v[126:129], v[122:125], v[0:15]
	ds_read_b128 v[114:117], v108 offset:32768
	ds_read_b128 v[118:121], v109 offset:49152
	ds_read_b128 v[122:125], v108 offset:36864
	ds_read_b128 v[126:129], v109 offset:53248
	s_waitcnt lgkmcnt(0)
	v_mfma_f32_32x32x16_bf16 v[48:63], v[118:121], v[114:117], v[48:63]
	v_mfma_f32_32x32x16_bf16 v[32:47], v[126:129], v[114:117], v[32:47]
	v_mfma_f32_32x32x16_bf16 v[16:31], v[118:121], v[122:125], v[16:31]
	v_mfma_f32_32x32x16_bf16 v[0:15], v[126:129], v[122:125], v[0:15]
	ds_read_b128 v[114:117], v110 offset:32768
	ds_read_b128 v[118:121], v111 offset:49152
	ds_read_b128 v[122:125], v110 offset:36864
	ds_read_b128 v[126:129], v111 offset:53248
	s_waitcnt lgkmcnt(0)
	v_mfma_f32_32x32x16_bf16 v[48:63], v[118:121], v[114:117], v[48:63]
	v_mfma_f32_32x32x16_bf16 v[32:47], v[126:129], v[114:117], v[32:47]
	v_mfma_f32_32x32x16_bf16 v[16:31], v[118:121], v[122:125], v[16:31]
	v_mfma_f32_32x32x16_bf16 v[0:15], v[126:129], v[122:125], v[0:15]
	ds_read_b128 v[114:117], v112 offset:32768
	ds_read_b128 v[118:121], v113 offset:49152
	ds_read_b128 v[122:125], v112 offset:36864
	ds_read_b128 v[126:129], v113 offset:53248
	s_waitcnt vmcnt(0)
	s_waitcnt vmcnt(0) lgkmcnt(0)
	s_barrier
	v_mfma_f32_32x32x16_bf16 v[48:63], v[118:121], v[114:117], v[48:63]
	v_mfma_f32_32x32x16_bf16 v[32:47], v[126:129], v[114:117], v[32:47]
	global_load_lds_dwordx4 v64, s[98:99]
	s_mov_b32 m0, s15
	s_nop 0
	global_load_lds_dwordx4 v66, s[98:99]
	s_mov_b32 m0, s72
	v_mfma_f32_32x32x16_bf16 v[16:31], v[118:121], v[122:125], v[16:31]
	global_load_lds_dwordx4 v68, s[98:99]
	s_mov_b32 m0, s73
	s_nop 0
	global_load_lds_dwordx4 v70, s[98:99]
	s_mov_b32 m0, s95
	v_mfma_f32_32x32x16_bf16 v[0:15], v[126:129], v[122:125], v[0:15]
	global_load_lds_dwordx4 v64, s[100:101]
	s_mov_b32 m0, s97
	s_nop 0
	global_load_lds_dwordx4 v66, s[100:101]
	s_mov_b32 m0, s28
	s_nop 0
	global_load_lds_dwordx4 v68, s[100:101]
	s_mov_b32 m0, s84
	s_nop 0
	global_load_lds_dwordx4 v70, s[100:101]
	s_add_u32 s98, s98, 0x80
	s_addc_u32 s99, s99, 0
	s_add_u32 s100, s100, 0x80
	s_addc_u32 s101, s101, 0
	ds_read_b128 v[114:117], v106
	ds_read_b128 v[118:121], v107 offset:16384
	ds_read_b128 v[122:125], v106 offset:4096
	ds_read_b128 v[126:129], v107 offset:20480
	s_waitcnt lgkmcnt(0)
	v_mfma_f32_32x32x16_bf16 v[48:63], v[118:121], v[114:117], v[48:63]
	s_mov_b32 m0, s68
	v_mfma_f32_32x32x16_bf16 v[32:47], v[126:129], v[114:117], v[32:47]
	v_mfma_f32_32x32x16_bf16 v[16:31], v[118:121], v[122:125], v[16:31]
	v_mfma_f32_32x32x16_bf16 v[0:15], v[126:129], v[122:125], v[0:15]
	ds_read_b128 v[114:117], v108
	ds_read_b128 v[118:121], v109 offset:16384
	ds_read_b128 v[122:125], v108 offset:4096
	ds_read_b128 v[126:129], v109 offset:20480
	s_waitcnt lgkmcnt(0)
	v_mfma_f32_32x32x16_bf16 v[48:63], v[118:121], v[114:117], v[48:63]
	v_mfma_f32_32x32x16_bf16 v[32:47], v[126:129], v[114:117], v[32:47]
	v_mfma_f32_32x32x16_bf16 v[16:31], v[118:121], v[122:125], v[16:31]
	v_mfma_f32_32x32x16_bf16 v[0:15], v[126:129], v[122:125], v[0:15]
	ds_read_b128 v[114:117], v110
	ds_read_b128 v[118:121], v111 offset:16384
	ds_read_b128 v[122:125], v110 offset:4096
	ds_read_b128 v[126:129], v111 offset:20480
	s_waitcnt lgkmcnt(0)
	v_mfma_f32_32x32x16_bf16 v[48:63], v[118:121], v[114:117], v[48:63]
	v_mfma_f32_32x32x16_bf16 v[32:47], v[126:129], v[114:117], v[32:47]
	v_mfma_f32_32x32x16_bf16 v[16:31], v[118:121], v[122:125], v[16:31]
	v_mfma_f32_32x32x16_bf16 v[0:15], v[126:129], v[122:125], v[0:15]
	ds_read_b128 v[114:117], v112
	ds_read_b128 v[118:121], v113 offset:16384
	ds_read_b128 v[122:125], v112 offset:4096
	ds_read_b128 v[126:129], v113 offset:20480
	s_waitcnt vmcnt(0)
	s_waitcnt vmcnt(0) lgkmcnt(0)
	s_barrier
	v_mfma_f32_32x32x16_bf16 v[48:63], v[118:121], v[114:117], v[48:63]
	v_mfma_f32_32x32x16_bf16 v[32:47], v[126:129], v[114:117], v[32:47]
	global_load_lds_dwordx4 v64, s[98:99]
	s_mov_b32 m0, s69
	s_nop 0
	global_load_lds_dwordx4 v66, s[98:99]
	s_mov_b32 m0, s70
	v_mfma_f32_32x32x16_bf16 v[16:31], v[118:121], v[122:125], v[16:31]
	global_load_lds_dwordx4 v68, s[98:99]
	s_mov_b32 m0, s71
	s_nop 0
	global_load_lds_dwordx4 v70, s[98:99]
	s_mov_b32 m0, s29
	v_mfma_f32_32x32x16_bf16 v[0:15], v[126:129], v[122:125], v[0:15]
	global_load_lds_dwordx4 v64, s[100:101]
	s_mov_b32 m0, s85
	s_nop 0
	global_load_lds_dwordx4 v66, s[100:101]
	s_mov_b32 m0, s86
	s_nop 0
	global_load_lds_dwordx4 v68, s[100:101]
	s_mov_b32 m0, s87
	s_nop 0
	global_load_lds_dwordx4 v70, s[100:101]
	s_add_u32 s98, s98, 0x80
	s_addc_u32 s99, s99, 0
	s_add_u32 s100, s100, 0x80
	s_addc_u32 s101, s101, 0
	ds_read_b128 v[114:117], v106 offset:32768
	ds_read_b128 v[118:121], v107 offset:49152
	ds_read_b128 v[122:125], v106 offset:36864
	ds_read_b128 v[126:129], v107 offset:53248
	s_waitcnt lgkmcnt(0)
	v_mfma_f32_32x32x16_bf16 v[48:63], v[118:121], v[114:117], v[48:63]
	s_mov_b32 m0, s14
	v_mfma_f32_32x32x16_bf16 v[32:47], v[126:129], v[114:117], v[32:47]
	v_mfma_f32_32x32x16_bf16 v[16:31], v[118:121], v[122:125], v[16:31]
	v_mfma_f32_32x32x16_bf16 v[0:15], v[126:129], v[122:125], v[0:15]
	ds_read_b128 v[114:117], v108 offset:32768
	ds_read_b128 v[118:121], v109 offset:49152
	ds_read_b128 v[122:125], v108 offset:36864
	ds_read_b128 v[126:129], v109 offset:53248
	s_waitcnt lgkmcnt(0)
	v_mfma_f32_32x32x16_bf16 v[48:63], v[118:121], v[114:117], v[48:63]
	v_mfma_f32_32x32x16_bf16 v[32:47], v[126:129], v[114:117], v[32:47]
	v_mfma_f32_32x32x16_bf16 v[16:31], v[118:121], v[122:125], v[16:31]
	v_mfma_f32_32x32x16_bf16 v[0:15], v[126:129], v[122:125], v[0:15]
	ds_read_b128 v[114:117], v110 offset:32768
	ds_read_b128 v[118:121], v111 offset:49152
	ds_read_b128 v[122:125], v110 offset:36864
	ds_read_b128 v[126:129], v111 offset:53248
	s_waitcnt lgkmcnt(0)
	v_mfma_f32_32x32x16_bf16 v[48:63], v[118:121], v[114:117], v[48:63]
	v_mfma_f32_32x32x16_bf16 v[32:47], v[126:129], v[114:117], v[32:47]
	v_mfma_f32_32x32x16_bf16 v[16:31], v[118:121], v[122:125], v[16:31]
	v_mfma_f32_32x32x16_bf16 v[0:15], v[126:129], v[122:125], v[0:15]
	ds_read_b128 v[114:117], v112 offset:32768
	ds_read_b128 v[118:121], v113 offset:49152
	ds_read_b128 v[122:125], v112 offset:36864
	ds_read_b128 v[126:129], v113 offset:53248
	s_waitcnt vmcnt(0)
	s_waitcnt vmcnt(0) lgkmcnt(0)
	s_barrier
	v_mfma_f32_32x32x16_bf16 v[48:63], v[118:121], v[114:117], v[48:63]
	v_mfma_f32_32x32x16_bf16 v[32:47], v[126:129], v[114:117], v[32:47]
	global_load_lds_dwordx4 v64, s[98:99]
	s_mov_b32 m0, s15
	s_nop 0
	global_load_lds_dwordx4 v66, s[98:99]
	s_mov_b32 m0, s72
	v_mfma_f32_32x32x16_bf16 v[16:31], v[118:121], v[122:125], v[16:31]
	global_load_lds_dwordx4 v68, s[98:99]
	s_mov_b32 m0, s73
	s_nop 0
	global_load_lds_dwordx4 v70, s[98:99]
	s_mov_b32 m0, s95
	v_mfma_f32_32x32x16_bf16 v[0:15], v[126:129], v[122:125], v[0:15]
	global_load_lds_dwordx4 v64, s[100:101]
	s_mov_b32 m0, s97
	s_nop 0
	global_load_lds_dwordx4 v66, s[100:101]
	s_mov_b32 m0, s28
	s_nop 0
	global_load_lds_dwordx4 v68, s[100:101]
	s_mov_b32 m0, s84
	s_nop 0
	global_load_lds_dwordx4 v70, s[100:101]
	s_add_u32 s98, s98, 0x80
	s_addc_u32 s99, s99, 0
	s_add_u32 s100, s100, 0x80
	s_addc_u32 s101, s101, 0
	ds_read_b128 v[114:117], v106
	ds_read_b128 v[118:121], v107 offset:16384
	ds_read_b128 v[122:125], v106 offset:4096
	ds_read_b128 v[126:129], v107 offset:20480
	s_waitcnt lgkmcnt(0)
	v_mfma_f32_32x32x16_bf16 v[48:63], v[118:121], v[114:117], v[48:63]
	s_mov_b32 m0, s68
	v_readfirstlane_b32 s68, v96
	v_mfma_f32_32x32x16_bf16 v[32:47], v[126:129], v[114:117], v[32:47]
	v_mfma_f32_32x32x16_bf16 v[16:31], v[118:121], v[122:125], v[16:31]
	v_mfma_f32_32x32x16_bf16 v[0:15], v[126:129], v[122:125], v[0:15]
	ds_read_b128 v[114:117], v108
	ds_read_b128 v[118:121], v109 offset:16384
	ds_read_b128 v[122:125], v108 offset:4096
	ds_read_b128 v[126:129], v109 offset:20480
	s_waitcnt lgkmcnt(0)
	v_mfma_f32_32x32x16_bf16 v[48:63], v[118:121], v[114:117], v[48:63]
	v_mfma_f32_32x32x16_bf16 v[32:47], v[126:129], v[114:117], v[32:47]
	v_mfma_f32_32x32x16_bf16 v[16:31], v[118:121], v[122:125], v[16:31]
	v_mfma_f32_32x32x16_bf16 v[0:15], v[126:129], v[122:125], v[0:15]
	ds_read_b128 v[114:117], v110
	ds_read_b128 v[118:121], v111 offset:16384
	ds_read_b128 v[122:125], v110 offset:4096
	ds_read_b128 v[126:129], v111 offset:20480
	s_waitcnt lgkmcnt(0)
	v_mfma_f32_32x32x16_bf16 v[48:63], v[118:121], v[114:117], v[48:63]
	v_mfma_f32_32x32x16_bf16 v[32:47], v[126:129], v[114:117], v[32:47]
	v_mfma_f32_32x32x16_bf16 v[16:31], v[118:121], v[122:125], v[16:31]
	v_mfma_f32_32x32x16_bf16 v[0:15], v[126:129], v[122:125], v[0:15]
	ds_read_b128 v[114:117], v112
	ds_read_b128 v[118:121], v113 offset:16384
	ds_read_b128 v[122:125], v112 offset:4096
	ds_read_b128 v[126:129], v113 offset:20480
	s_waitcnt vmcnt(0)
	s_waitcnt vmcnt(0) lgkmcnt(0)
	s_barrier
	v_mfma_f32_32x32x16_bf16 v[48:63], v[118:121], v[114:117], v[48:63]
	v_mfma_f32_32x32x16_bf16 v[32:47], v[126:129], v[114:117], v[32:47]
	global_load_lds_dwordx4 v64, s[98:99]
	s_mov_b32 m0, s69
	v_readfirstlane_b32 s69, v97
	global_load_lds_dwordx4 v66, s[98:99]
	s_mov_b32 m0, s70
	v_mfma_f32_32x32x16_bf16 v[16:31], v[118:121], v[122:125], v[16:31]
	global_load_lds_dwordx4 v68, s[98:99]
	s_mov_b32 m0, s71
	v_readfirstlane_b32 s70, v98
	global_load_lds_dwordx4 v70, s[98:99]
	s_mov_b32 m0, s29
	v_mfma_f32_32x32x16_bf16 v[0:15], v[126:129], v[122:125], v[0:15]
	global_load_lds_dwordx4 v64, s[100:101]
	s_mov_b32 m0, s85
	v_readfirstlane_b32 s29, v93
	global_load_lds_dwordx4 v66, s[100:101]
	s_mov_b32 m0, s86
	v_readfirstlane_b32 s71, v99
	global_load_lds_dwordx4 v68, s[100:101]
	s_mov_b32 m0, s87
	v_readfirstlane_b32 s85, v103
	global_load_lds_dwordx4 v70, s[100:101]
	s_add_u32 s98, s98, 0x80
	s_addc_u32 s99, s99, 0
	s_add_u32 s100, s100, 0x80
	s_addc_u32 s101, s101, 0
	ds_read_b128 v[114:117], v106 offset:32768
	ds_read_b128 v[118:121], v107 offset:49152
	ds_read_b128 v[122:125], v106 offset:36864
	ds_read_b128 v[126:129], v107 offset:53248
	s_waitcnt lgkmcnt(0)
	v_mfma_f32_32x32x16_bf16 v[48:63], v[118:121], v[114:117], v[48:63]
	s_mov_b32 m0, s14
	v_readfirstlane_b32 s14, v88
	v_readfirstlane_b32 s86, v104
	v_readfirstlane_b32 s87, v105
	v_mfma_f32_32x32x16_bf16 v[32:47], v[126:129], v[114:117], v[32:47]
	v_mfma_f32_32x32x16_bf16 v[16:31], v[118:121], v[122:125], v[16:31]
	v_mfma_f32_32x32x16_bf16 v[0:15], v[126:129], v[122:125], v[0:15]
	ds_read_b128 v[114:117], v108 offset:32768
	ds_read_b128 v[118:121], v109 offset:49152
	ds_read_b128 v[122:125], v108 offset:36864
	ds_read_b128 v[126:129], v109 offset:53248
	s_waitcnt lgkmcnt(0)
	v_mfma_f32_32x32x16_bf16 v[48:63], v[118:121], v[114:117], v[48:63]
	v_mfma_f32_32x32x16_bf16 v[32:47], v[126:129], v[114:117], v[32:47]
	v_mfma_f32_32x32x16_bf16 v[16:31], v[118:121], v[122:125], v[16:31]
	v_mfma_f32_32x32x16_bf16 v[0:15], v[126:129], v[122:125], v[0:15]
	ds_read_b128 v[114:117], v110 offset:32768
	ds_read_b128 v[118:121], v111 offset:49152
	ds_read_b128 v[122:125], v110 offset:36864
	ds_read_b128 v[126:129], v111 offset:53248
	s_waitcnt lgkmcnt(0)
	v_mfma_f32_32x32x16_bf16 v[48:63], v[118:121], v[114:117], v[48:63]
	v_mfma_f32_32x32x16_bf16 v[32:47], v[126:129], v[114:117], v[32:47]
	v_mfma_f32_32x32x16_bf16 v[16:31], v[118:121], v[122:125], v[16:31]
	v_mfma_f32_32x32x16_bf16 v[0:15], v[126:129], v[122:125], v[0:15]
	ds_read_b128 v[114:117], v112 offset:32768
	ds_read_b128 v[118:121], v113 offset:49152
	ds_read_b128 v[122:125], v112 offset:36864
	ds_read_b128 v[126:129], v113 offset:53248
	s_waitcnt vmcnt(0)
	s_waitcnt vmcnt(0) lgkmcnt(0)
	s_barrier
	v_mfma_f32_32x32x16_bf16 v[48:63], v[118:121], v[114:117], v[48:63]
	v_mfma_f32_32x32x16_bf16 v[32:47], v[126:129], v[114:117], v[32:47]
	global_load_lds_dwordx4 v64, s[98:99]
	s_mov_b32 m0, s15
	v_readfirstlane_b32 s15, v91
	global_load_lds_dwordx4 v66, s[98:99]
	s_mov_b32 m0, s72
	v_mfma_f32_32x32x16_bf16 v[16:31], v[118:121], v[122:125], v[16:31]
	global_load_lds_dwordx4 v68, s[98:99]
	s_mov_b32 m0, s73
	v_readfirstlane_b32 s72, v100
	global_load_lds_dwordx4 v70, s[98:99]
	s_mov_b32 m0, s95
	v_mfma_f32_32x32x16_bf16 v[0:15], v[126:129], v[122:125], v[0:15]
	global_load_lds_dwordx4 v64, s[100:101]
	s_mov_b32 m0, s97
	v_readfirstlane_b32 s73, v101
	global_load_lds_dwordx4 v66, s[100:101]
	s_mov_b32 m0, s28
	v_readfirstlane_b32 s28, v92
	global_load_lds_dwordx4 v68, s[100:101]
	s_mov_b32 m0, s84
	v_readfirstlane_b32 s84, v102
	global_load_lds_dwordx4 v70, s[100:101]
	s_add_u32 s98, s98, 0x80
	s_addc_u32 s99, s99, 0
	s_add_u32 s100, s100, 0x80
	s_addc_u32 s101, s101, 0
	ds_read_b128 v[114:117], v106
	ds_read_b128 v[118:121], v107 offset:16384
	ds_read_b128 v[122:125], v106 offset:4096
	ds_read_b128 v[126:129], v107 offset:20480
	s_waitcnt lgkmcnt(0)
	v_mfma_f32_32x32x16_bf16 v[48:63], v[118:121], v[114:117], v[48:63]
	s_mov_b32 m0, s14
	v_mfma_f32_32x32x16_bf16 v[32:47], v[126:129], v[114:117], v[32:47]
	v_mfma_f32_32x32x16_bf16 v[16:31], v[118:121], v[122:125], v[16:31]
	v_mfma_f32_32x32x16_bf16 v[0:15], v[126:129], v[122:125], v[0:15]
	ds_read_b128 v[114:117], v108
	ds_read_b128 v[118:121], v109 offset:16384
	ds_read_b128 v[122:125], v108 offset:4096
	ds_read_b128 v[126:129], v109 offset:20480
	s_waitcnt lgkmcnt(0)
	v_mfma_f32_32x32x16_bf16 v[48:63], v[118:121], v[114:117], v[48:63]
	v_mfma_f32_32x32x16_bf16 v[32:47], v[126:129], v[114:117], v[32:47]
	v_mfma_f32_32x32x16_bf16 v[16:31], v[118:121], v[122:125], v[16:31]
	v_mfma_f32_32x32x16_bf16 v[0:15], v[126:129], v[122:125], v[0:15]
	ds_read_b128 v[114:117], v110
	ds_read_b128 v[118:121], v111 offset:16384
	ds_read_b128 v[122:125], v110 offset:4096
	ds_read_b128 v[126:129], v111 offset:20480
	s_waitcnt lgkmcnt(0)
	v_mfma_f32_32x32x16_bf16 v[48:63], v[118:121], v[114:117], v[48:63]
	v_mfma_f32_32x32x16_bf16 v[32:47], v[126:129], v[114:117], v[32:47]
	v_mfma_f32_32x32x16_bf16 v[16:31], v[118:121], v[122:125], v[16:31]
	v_mfma_f32_32x32x16_bf16 v[0:15], v[126:129], v[122:125], v[0:15]
	ds_read_b128 v[114:117], v112
	ds_read_b128 v[118:121], v113 offset:16384
	ds_read_b128 v[122:125], v112 offset:4096
	ds_read_b128 v[126:129], v113 offset:20480
	s_waitcnt vmcnt(0)
	s_waitcnt vmcnt(0) lgkmcnt(0)
	s_barrier
	v_mfma_f32_32x32x16_bf16 v[48:63], v[118:121], v[114:117], v[48:63]
	v_mfma_f32_32x32x16_bf16 v[32:47], v[126:129], v[114:117], v[32:47]
	global_load_lds_dwordx4 v64, s[98:99]
	s_mov_b32 m0, s15
	s_nop 0
	global_load_lds_dwordx4 v66, s[98:99]
	s_mov_b32 m0, s28
	v_mfma_f32_32x32x16_bf16 v[16:31], v[118:121], v[122:125], v[16:31]
	global_load_lds_dwordx4 v68, s[98:99]
	s_mov_b32 m0, s29
	s_nop 0
	global_load_lds_dwordx4 v70, s[98:99]
	s_mov_b32 m0, s34
	v_mfma_f32_32x32x16_bf16 v[0:15], v[126:129], v[122:125], v[0:15]
	global_load_lds_dwordx4 v64, s[100:101]
	s_mov_b32 m0, s35
	s_nop 0
	global_load_lds_dwordx4 v66, s[100:101]
	s_mov_b32 m0, s68
	s_nop 0
	global_load_lds_dwordx4 v68, s[100:101]
	s_mov_b32 m0, s69
	s_nop 0
	global_load_lds_dwordx4 v70, s[100:101]
	s_add_u32 s98, s98, 0x80
	s_addc_u32 s99, s99, 0
	s_add_u32 s100, s100, 0x80
	s_addc_u32 s101, s101, 0
	ds_read_b128 v[114:117], v106 offset:32768
	ds_read_b128 v[118:121], v107 offset:49152
	ds_read_b128 v[122:125], v106 offset:36864
	ds_read_b128 v[126:129], v107 offset:53248
	s_waitcnt lgkmcnt(0)
	v_mfma_f32_32x32x16_bf16 v[48:63], v[118:121], v[114:117], v[48:63]
	s_mov_b32 m0, s70
	v_mfma_f32_32x32x16_bf16 v[32:47], v[126:129], v[114:117], v[32:47]
	v_mfma_f32_32x32x16_bf16 v[16:31], v[118:121], v[122:125], v[16:31]
	v_mfma_f32_32x32x16_bf16 v[0:15], v[126:129], v[122:125], v[0:15]
	ds_read_b128 v[114:117], v108 offset:32768
	ds_read_b128 v[118:121], v109 offset:49152
	ds_read_b128 v[122:125], v108 offset:36864
	ds_read_b128 v[126:129], v109 offset:53248
	s_waitcnt lgkmcnt(0)
	v_mfma_f32_32x32x16_bf16 v[48:63], v[118:121], v[114:117], v[48:63]
	v_mfma_f32_32x32x16_bf16 v[32:47], v[126:129], v[114:117], v[32:47]
	v_mfma_f32_32x32x16_bf16 v[16:31], v[118:121], v[122:125], v[16:31]
	v_mfma_f32_32x32x16_bf16 v[0:15], v[126:129], v[122:125], v[0:15]
	ds_read_b128 v[114:117], v110 offset:32768
	ds_read_b128 v[118:121], v111 offset:49152
	ds_read_b128 v[122:125], v110 offset:36864
	ds_read_b128 v[126:129], v111 offset:53248
	s_waitcnt lgkmcnt(0)
	v_mfma_f32_32x32x16_bf16 v[48:63], v[118:121], v[114:117], v[48:63]
	v_mfma_f32_32x32x16_bf16 v[32:47], v[126:129], v[114:117], v[32:47]
	v_mfma_f32_32x32x16_bf16 v[16:31], v[118:121], v[122:125], v[16:31]
	v_mfma_f32_32x32x16_bf16 v[0:15], v[126:129], v[122:125], v[0:15]
	ds_read_b128 v[114:117], v112 offset:32768
	ds_read_b128 v[118:121], v113 offset:49152
	ds_read_b128 v[122:125], v112 offset:36864
	ds_read_b128 v[126:129], v113 offset:53248
	s_waitcnt vmcnt(0)
	s_waitcnt vmcnt(0) lgkmcnt(0)
	s_barrier
	v_mfma_f32_32x32x16_bf16 v[48:63], v[118:121], v[114:117], v[48:63]
	v_mfma_f32_32x32x16_bf16 v[32:47], v[126:129], v[114:117], v[32:47]
	global_load_lds_dwordx4 v64, s[98:99]
	s_mov_b32 m0, s71
	s_nop 0
	global_load_lds_dwordx4 v66, s[98:99]
	s_mov_b32 m0, s72
	v_mfma_f32_32x32x16_bf16 v[16:31], v[118:121], v[122:125], v[16:31]
	global_load_lds_dwordx4 v68, s[98:99]
	s_mov_b32 m0, s73
	s_nop 0
	global_load_lds_dwordx4 v70, s[98:99]
	s_mov_b32 m0, s84
	v_mfma_f32_32x32x16_bf16 v[0:15], v[126:129], v[122:125], v[0:15]
	global_load_lds_dwordx4 v64, s[100:101]
	s_mov_b32 m0, s85
	s_nop 0
	global_load_lds_dwordx4 v66, s[100:101]
	s_mov_b32 m0, s86
	s_nop 0
	global_load_lds_dwordx4 v68, s[100:101]
	s_mov_b32 m0, s87
	s_nop 0
	global_load_lds_dwordx4 v70, s[100:101]
	s_add_u32 s98, s98, 0x80
	s_addc_u32 s99, s99, 0
	s_add_u32 s100, s100, 0x80
	s_addc_u32 s101, s101, 0
	ds_read_b128 v[114:117], v106
	ds_read_b128 v[118:121], v107 offset:16384
	ds_read_b128 v[122:125], v106 offset:4096
	ds_read_b128 v[126:129], v107 offset:20480
	s_waitcnt lgkmcnt(0)
	v_mfma_f32_32x32x16_bf16 v[48:63], v[118:121], v[114:117], v[48:63]
	s_mov_b32 m0, s14
	v_mfma_f32_32x32x16_bf16 v[32:47], v[126:129], v[114:117], v[32:47]
	v_mfma_f32_32x32x16_bf16 v[16:31], v[118:121], v[122:125], v[16:31]
	v_mfma_f32_32x32x16_bf16 v[0:15], v[126:129], v[122:125], v[0:15]
	ds_read_b128 v[114:117], v108
	ds_read_b128 v[118:121], v109 offset:16384
	ds_read_b128 v[122:125], v108 offset:4096
	ds_read_b128 v[126:129], v109 offset:20480
	s_waitcnt lgkmcnt(0)
	v_mfma_f32_32x32x16_bf16 v[48:63], v[118:121], v[114:117], v[48:63]
	v_mfma_f32_32x32x16_bf16 v[32:47], v[126:129], v[114:117], v[32:47]
	v_mfma_f32_32x32x16_bf16 v[16:31], v[118:121], v[122:125], v[16:31]
	v_mfma_f32_32x32x16_bf16 v[0:15], v[126:129], v[122:125], v[0:15]
	ds_read_b128 v[114:117], v110
	ds_read_b128 v[118:121], v111 offset:16384
	ds_read_b128 v[122:125], v110 offset:4096
	ds_read_b128 v[126:129], v111 offset:20480
	s_waitcnt lgkmcnt(0)
	v_mfma_f32_32x32x16_bf16 v[48:63], v[118:121], v[114:117], v[48:63]
	v_mfma_f32_32x32x16_bf16 v[32:47], v[126:129], v[114:117], v[32:47]
	v_mfma_f32_32x32x16_bf16 v[16:31], v[118:121], v[122:125], v[16:31]
	v_mfma_f32_32x32x16_bf16 v[0:15], v[126:129], v[122:125], v[0:15]
	ds_read_b128 v[114:117], v112
	ds_read_b128 v[118:121], v113 offset:16384
	ds_read_b128 v[122:125], v112 offset:4096
	ds_read_b128 v[126:129], v113 offset:20480
	s_waitcnt vmcnt(0)
	s_waitcnt vmcnt(0) lgkmcnt(0)
	s_barrier
	v_mfma_f32_32x32x16_bf16 v[48:63], v[118:121], v[114:117], v[48:63]
	v_mfma_f32_32x32x16_bf16 v[32:47], v[126:129], v[114:117], v[32:47]
	global_load_lds_dwordx4 v64, s[98:99]
	s_mov_b32 m0, s15
	s_nop 0
	global_load_lds_dwordx4 v66, s[98:99]
	s_mov_b32 m0, s28
	v_mfma_f32_32x32x16_bf16 v[16:31], v[118:121], v[122:125], v[16:31]
	global_load_lds_dwordx4 v68, s[98:99]
	s_mov_b32 m0, s29
	s_nop 0
	global_load_lds_dwordx4 v70, s[98:99]
	s_mov_b32 m0, s34
	v_mfma_f32_32x32x16_bf16 v[0:15], v[126:129], v[122:125], v[0:15]
	global_load_lds_dwordx4 v64, s[100:101]
	s_mov_b32 m0, s35
	s_nop 0
	global_load_lds_dwordx4 v66, s[100:101]
	s_mov_b32 m0, s68
	s_nop 0
	global_load_lds_dwordx4 v68, s[100:101]
	s_mov_b32 m0, s69
	s_nop 0
	global_load_lds_dwordx4 v70, s[100:101]
	s_add_u32 s98, s98, 0x80
	s_addc_u32 s99, s99, 0
	s_add_u32 s100, s100, 0x80
	s_addc_u32 s101, s101, 0
	ds_read_b128 v[114:117], v106 offset:32768
	ds_read_b128 v[118:121], v107 offset:49152
	ds_read_b128 v[122:125], v106 offset:36864
	ds_read_b128 v[126:129], v107 offset:53248
	s_waitcnt lgkmcnt(0)
	v_mfma_f32_32x32x16_bf16 v[48:63], v[118:121], v[114:117], v[48:63]
	s_mov_b32 m0, s70
	v_mfma_f32_32x32x16_bf16 v[32:47], v[126:129], v[114:117], v[32:47]
	v_mfma_f32_32x32x16_bf16 v[16:31], v[118:121], v[122:125], v[16:31]
	v_mfma_f32_32x32x16_bf16 v[0:15], v[126:129], v[122:125], v[0:15]
	ds_read_b128 v[114:117], v108 offset:32768
	ds_read_b128 v[118:121], v109 offset:49152
	ds_read_b128 v[122:125], v108 offset:36864
	ds_read_b128 v[126:129], v109 offset:53248
	s_waitcnt lgkmcnt(0)
	v_mfma_f32_32x32x16_bf16 v[48:63], v[118:121], v[114:117], v[48:63]
	v_mfma_f32_32x32x16_bf16 v[32:47], v[126:129], v[114:117], v[32:47]
	v_mfma_f32_32x32x16_bf16 v[16:31], v[118:121], v[122:125], v[16:31]
	v_mfma_f32_32x32x16_bf16 v[0:15], v[126:129], v[122:125], v[0:15]
	ds_read_b128 v[114:117], v110 offset:32768
	ds_read_b128 v[118:121], v111 offset:49152
	ds_read_b128 v[122:125], v110 offset:36864
	ds_read_b128 v[126:129], v111 offset:53248
	s_waitcnt lgkmcnt(0)
	v_mfma_f32_32x32x16_bf16 v[48:63], v[118:121], v[114:117], v[48:63]
	v_mfma_f32_32x32x16_bf16 v[32:47], v[126:129], v[114:117], v[32:47]
	v_mfma_f32_32x32x16_bf16 v[16:31], v[118:121], v[122:125], v[16:31]
	v_mfma_f32_32x32x16_bf16 v[0:15], v[126:129], v[122:125], v[0:15]
	ds_read_b128 v[114:117], v112 offset:32768
	ds_read_b128 v[118:121], v113 offset:49152
	ds_read_b128 v[122:125], v112 offset:36864
	ds_read_b128 v[126:129], v113 offset:53248
	s_waitcnt vmcnt(0)
	s_waitcnt vmcnt(0) lgkmcnt(0)
	s_barrier
	v_mfma_f32_32x32x16_bf16 v[48:63], v[118:121], v[114:117], v[48:63]
	v_mfma_f32_32x32x16_bf16 v[32:47], v[126:129], v[114:117], v[32:47]
	global_load_lds_dwordx4 v64, s[98:99]
	s_mov_b32 m0, s71
	s_nop 0
	global_load_lds_dwordx4 v66, s[98:99]
	s_mov_b32 m0, s72
	v_mfma_f32_32x32x16_bf16 v[16:31], v[118:121], v[122:125], v[16:31]
	global_load_lds_dwordx4 v68, s[98:99]
	s_mov_b32 m0, s73
	s_nop 0
	global_load_lds_dwordx4 v70, s[98:99]
	s_mov_b32 m0, s84
	v_mfma_f32_32x32x16_bf16 v[0:15], v[126:129], v[122:125], v[0:15]
	global_load_lds_dwordx4 v64, s[100:101]
	s_mov_b32 m0, s85
	s_nop 0
	global_load_lds_dwordx4 v66, s[100:101]
	s_mov_b32 m0, s86
	s_nop 0
	global_load_lds_dwordx4 v68, s[100:101]
	s_mov_b32 m0, s87
	s_nop 0
	global_load_lds_dwordx4 v70, s[100:101]
	s_add_u32 s98, s98, 0x80
	s_addc_u32 s99, s99, 0
	s_add_u32 s100, s100, 0x80
	s_addc_u32 s101, s101, 0
	ds_read_b128 v[114:117], v106
	ds_read_b128 v[118:121], v107 offset:16384
	ds_read_b128 v[122:125], v106 offset:4096
	ds_read_b128 v[126:129], v107 offset:20480
	s_waitcnt lgkmcnt(0)
	v_mfma_f32_32x32x16_bf16 v[48:63], v[118:121], v[114:117], v[48:63]
	s_mov_b32 m0, s14
	s_add_i32 s14, s2, s13
	s_cmpk_lt_i32 s14, 0x400
	v_mfma_f32_32x32x16_bf16 v[32:47], v[126:129], v[114:117], v[32:47]
	v_mfma_f32_32x32x16_bf16 v[16:31], v[118:121], v[122:125], v[16:31]
	v_mfma_f32_32x32x16_bf16 v[0:15], v[126:129], v[122:125], v[0:15]
	ds_read_b128 v[114:117], v108
	ds_read_b128 v[118:121], v109 offset:16384
	ds_read_b128 v[122:125], v108 offset:4096
	ds_read_b128 v[126:129], v109 offset:20480
	s_waitcnt lgkmcnt(0)
	v_mfma_f32_32x32x16_bf16 v[48:63], v[118:121], v[114:117], v[48:63]
	v_mfma_f32_32x32x16_bf16 v[32:47], v[126:129], v[114:117], v[32:47]
	v_mfma_f32_32x32x16_bf16 v[16:31], v[118:121], v[122:125], v[16:31]
	v_mfma_f32_32x32x16_bf16 v[0:15], v[126:129], v[122:125], v[0:15]
	ds_read_b128 v[114:117], v110
	ds_read_b128 v[118:121], v111 offset:16384
	ds_read_b128 v[122:125], v110 offset:4096
	ds_read_b128 v[126:129], v111 offset:20480
	s_waitcnt lgkmcnt(0)
	v_mfma_f32_32x32x16_bf16 v[48:63], v[118:121], v[114:117], v[48:63]
	v_mfma_f32_32x32x16_bf16 v[32:47], v[126:129], v[114:117], v[32:47]
	v_mfma_f32_32x32x16_bf16 v[16:31], v[118:121], v[122:125], v[16:31]
	v_mfma_f32_32x32x16_bf16 v[0:15], v[126:129], v[122:125], v[0:15]
	ds_read_b128 v[114:117], v112
	ds_read_b128 v[118:121], v113 offset:16384
	ds_read_b128 v[122:125], v112 offset:4096
	ds_read_b128 v[126:129], v113 offset:20480
	s_waitcnt vmcnt(0)
	s_waitcnt vmcnt(0) lgkmcnt(0)
	s_barrier
	v_mfma_f32_32x32x16_bf16 v[48:63], v[118:121], v[114:117], v[48:63]
	v_mfma_f32_32x32x16_bf16 v[32:47], v[126:129], v[114:117], v[32:47]
	global_load_lds_dwordx4 v64, s[98:99]
	s_mov_b32 m0, s15
	s_nop 0
	global_load_lds_dwordx4 v66, s[98:99]
	s_mov_b32 m0, s28
	v_mfma_f32_32x32x16_bf16 v[16:31], v[118:121], v[122:125], v[16:31]
	global_load_lds_dwordx4 v68, s[98:99]
	s_mov_b32 m0, s29
	s_nop 0
	global_load_lds_dwordx4 v70, s[98:99]
	s_mov_b32 m0, s34
	v_mfma_f32_32x32x16_bf16 v[0:15], v[126:129], v[122:125], v[0:15]
	global_load_lds_dwordx4 v64, s[100:101]
	s_mov_b32 m0, s35
	s_nop 0
	global_load_lds_dwordx4 v66, s[100:101]
	s_mov_b32 m0, s68
	s_nop 0
	global_load_lds_dwordx4 v68, s[100:101]
	s_mov_b32 m0, s69
	s_nop 0
	global_load_lds_dwordx4 v70, s[100:101]
	s_add_u32 s98, s98, 0x80
	s_addc_u32 s99, s99, 0
	s_add_u32 s100, s100, 0x80
	s_addc_u32 s101, s101, 0
	ds_read_b128 v[114:117], v106 offset:32768
	ds_read_b128 v[118:121], v107 offset:49152
	ds_read_b128 v[122:125], v106 offset:36864
	ds_read_b128 v[126:129], v107 offset:53248
	s_waitcnt lgkmcnt(0)
	v_mfma_f32_32x32x16_bf16 v[16:31], v[118:121], v[122:125], v[16:31]
	s_mov_b32 m0, s70
	v_mfma_f32_32x32x16_bf16 v[0:15], v[126:129], v[122:125], v[0:15]
	v_mfma_f32_32x32x16_bf16 v[32:47], v[126:129], v[114:117], v[32:47]
	v_mfma_f32_32x32x16_bf16 v[48:63], v[118:121], v[114:117], v[48:63]
	ds_read_b128 v[114:117], v108 offset:32768
	ds_read_b128 v[118:121], v109 offset:49152
	ds_read_b128 v[122:125], v108 offset:36864
	ds_read_b128 v[126:129], v109 offset:53248
	s_waitcnt lgkmcnt(0)
	v_mfma_f32_32x32x16_bf16 v[16:31], v[118:121], v[122:125], v[16:31]
	v_mfma_f32_32x32x16_bf16 v[0:15], v[126:129], v[122:125], v[0:15]
	v_mfma_f32_32x32x16_bf16 v[32:47], v[126:129], v[114:117], v[32:47]
	v_mfma_f32_32x32x16_bf16 v[48:63], v[118:121], v[114:117], v[48:63]
	ds_read_b128 v[114:117], v110 offset:32768
	ds_read_b128 v[118:121], v111 offset:49152
	ds_read_b128 v[122:125], v110 offset:36864
	ds_read_b128 v[126:129], v111 offset:53248
	s_waitcnt lgkmcnt(0)
	v_mfma_f32_32x32x16_bf16 v[16:31], v[118:121], v[122:125], v[16:31]
	v_mfma_f32_32x32x16_bf16 v[0:15], v[126:129], v[122:125], v[0:15]
	v_mfma_f32_32x32x16_bf16 v[32:47], v[126:129], v[114:117], v[32:47]
	v_mfma_f32_32x32x16_bf16 v[48:63], v[118:121], v[114:117], v[48:63]
	ds_read_b128 v[114:117], v112 offset:32768
	ds_read_b128 v[118:121], v113 offset:49152
	ds_read_b128 v[122:125], v112 offset:36864
	ds_read_b128 v[126:129], v113 offset:53248
	s_waitcnt vmcnt(0)
	s_waitcnt vmcnt(0) lgkmcnt(0)
	s_barrier
	global_load_lds_dwordx4 v64, s[98:99]
	s_mov_b32 m0, s71
	v_mfma_f32_32x32x16_bf16 v[16:31], v[118:121], v[122:125], v[16:31]
	global_load_lds_dwordx4 v66, s[98:99]
	s_mov_b32 m0, s72
	s_nop 0
	global_load_lds_dwordx4 v68, s[98:99]
	s_mov_b32 m0, s73
	v_mfma_f32_32x32x16_bf16 v[0:15], v[126:129], v[122:125], v[0:15]
	global_load_lds_dwordx4 v70, s[98:99]
	s_mov_b32 m0, s84
	s_nop 0
	global_load_lds_dwordx4 v64, s[100:101]
	s_mov_b32 m0, s85
	v_mfma_f32_32x32x16_bf16 v[32:47], v[126:129], v[114:117], v[32:47]
	global_load_lds_dwordx4 v66, s[100:101]
	s_mov_b32 m0, s86
	s_nop 0
	global_load_lds_dwordx4 v68, s[100:101]
	s_mov_b32 m0, s87
	v_mfma_f32_32x32x16_bf16 v[48:63], v[118:121], v[114:117], v[48:63]
	global_load_lds_dwordx4 v70, s[100:101]
	ds_read_b128 v[72:75], v106
	ds_read_b128 v[76:79], v107 offset:16384
	ds_read_b128 v[80:83], v106 offset:4096
	ds_read_b128 v[84:87], v107 offset:20480
	s_waitcnt lgkmcnt(0)
	v_mfma_f32_32x32x16_bf16 v[16:31], v[76:79], v[80:83], v[16:31]
	v_mfma_f32_32x32x16_bf16 v[0:15], v[84:87], v[80:83], v[0:15]
	v_mfma_f32_32x32x16_bf16 v[32:47], v[84:87], v[72:75], v[32:47]
	v_mfma_f32_32x32x16_bf16 v[48:63], v[76:79], v[72:75], v[48:63]
	ds_read_b128 v[72:75], v108
	ds_read_b128 v[76:79], v109 offset:16384
	ds_read_b128 v[80:83], v108 offset:4096
	ds_read_b128 v[84:87], v109 offset:20480
	s_waitcnt lgkmcnt(0)
	v_mfma_f32_32x32x16_bf16 v[16:31], v[76:79], v[80:83], v[16:31]
	v_mfma_f32_32x32x16_bf16 v[0:15], v[84:87], v[80:83], v[0:15]
	v_mfma_f32_32x32x16_bf16 v[32:47], v[84:87], v[72:75], v[32:47]
	v_mfma_f32_32x32x16_bf16 v[48:63], v[76:79], v[72:75], v[48:63]
	ds_read_b128 v[72:75], v110
	ds_read_b128 v[76:79], v111 offset:16384
	ds_read_b128 v[80:83], v110 offset:4096
	ds_read_b128 v[84:87], v111 offset:20480
	s_waitcnt lgkmcnt(0)
	v_mfma_f32_32x32x16_bf16 v[16:31], v[76:79], v[80:83], v[16:31]
	v_mfma_f32_32x32x16_bf16 v[0:15], v[84:87], v[80:83], v[0:15]
	v_mfma_f32_32x32x16_bf16 v[32:47], v[84:87], v[72:75], v[32:47]
	v_mfma_f32_32x32x16_bf16 v[48:63], v[76:79], v[72:75], v[48:63]
	ds_read_b128 v[72:75], v112
	ds_read_b128 v[76:79], v113 offset:16384
	ds_read_b128 v[80:83], v112 offset:4096
	ds_read_b128 v[84:87], v113 offset:20480
	s_waitcnt vmcnt(0)
	s_waitcnt vmcnt(0) lgkmcnt(0)
	s_barrier
	v_mfma_f32_32x32x16_bf16 v[16:31], v[76:79], v[80:83], v[16:31]
	v_mfma_f32_32x32x16_bf16 v[0:15], v[84:87], v[80:83], v[0:15]
	v_mfma_f32_32x32x16_bf16 v[32:47], v[84:87], v[72:75], v[32:47]
	v_mfma_f32_32x32x16_bf16 v[48:63], v[76:79], v[72:75], v[48:63]
	ds_read_b128 v[72:75], v113 offset:53248
	ds_read_b128 v[76:79], v112 offset:36864
	ds_read_b128 v[80:83], v113 offset:49152
	ds_read_b128 v[84:87], v112 offset:32768
	ds_read_b128 v[114:117], v111 offset:53248
	ds_read_b128 v[118:121], v110 offset:36864
	ds_read_b128 v[122:125], v111 offset:49152
	ds_read_b128 v[126:129], v110 offset:32768
	ds_read_b128 v[130:133], v109 offset:53248
	ds_read_b128 v[134:137], v108 offset:36864
	ds_read_b128 v[138:141], v109 offset:49152
	ds_read_b128 v[142:145], v108 offset:32768
	ds_read_b128 v[146:149], v107 offset:53248
	ds_read_b128 v[150:153], v106 offset:36864
	ds_read_b128 v[156:159], v107 offset:49152
	ds_read_b128 v[160:163], v106 offset:32768
	s_waitcnt vmcnt(0)
	s_waitcnt lgkmcnt(0)
	s_barrier
	v_mfma_f32_32x32x16_bf16 v[16:31], v[156:159], v[150:153], v[16:31]
	v_mfma_f32_32x32x16_bf16 v[0:15], v[146:149], v[150:153], v[0:15]
	v_mfma_f32_32x32x16_bf16 v[32:47], v[146:149], v[160:163], v[32:47]
	v_mfma_f32_32x32x16_bf16 v[48:63], v[156:159], v[160:163], v[48:63]
	v_mfma_f32_32x32x16_bf16 v[16:31], v[138:141], v[134:137], v[16:31]
	v_mfma_f32_32x32x16_bf16 v[0:15], v[130:133], v[134:137], v[0:15]
	v_mfma_f32_32x32x16_bf16 v[32:47], v[130:133], v[142:145], v[32:47]
	v_mfma_f32_32x32x16_bf16 v[48:63], v[138:141], v[142:145], v[48:63]
	v_mfma_f32_32x32x16_bf16 v[16:31], v[122:125], v[118:121], v[16:31]
	v_mfma_f32_32x32x16_bf16 v[0:15], v[114:117], v[118:121], v[0:15]
	v_mfma_f32_32x32x16_bf16 v[32:47], v[114:117], v[126:129], v[32:47]
	v_mfma_f32_32x32x16_bf16 v[48:63], v[122:125], v[126:129], v[48:63]
	v_mfma_f32_32x32x16_bf16 v[16:31], v[80:83], v[76:79], v[16:31]
	v_mfma_f32_32x32x16_bf16 v[0:15], v[72:75], v[76:79], v[0:15]
	v_add_u32_e32 v76, s94, v89
	v_ashrrev_i32_e32 v77, 31, v76
	v_mfma_f32_32x32x16_bf16 v[32:47], v[72:75], v[84:87], v[32:47]
	v_or_b32_e32 v72, s96, v90
	v_lshlrev_b64 v[74:75], 12, v[76:77]
	v_ashrrev_i32_e32 v73, 31, v72
	v_lshl_add_u64 v[78:79], s[52:53], 0, v[74:75]
	v_mfma_f32_32x32x16_bf16 v[48:63], v[80:83], v[84:87], v[48:63]
	v_lshlrev_b64 v[82:83], 2, v[72:73]
	v_lshl_add_u64 v[78:79], v[78:79], 0, v[82:83]
	v_lshl_add_u64 v[80:81], s[38:39], 0, v[74:75]
	v_lshl_add_u64 v[228:229], v[80:81], 0, v[82:83]
	v_or_b32_e32 v234, 32, v76
	v_ashrrev_i32_e32 v235, 31, v234
	v_lshlrev_b64 v[234:235], 12, v[234:235]
	v_lshl_add_u64 v[230:231], s[52:53], 0, v[234:235]
	v_lshl_add_u64 v[230:231], v[230:231], 0, v[82:83]
	v_lshl_add_u64 v[232:233], s[38:39], 0, v[234:235]
	v_lshl_add_u64 v[232:233], v[232:233], 0, v[82:83]
	s_waitcnt vmcnt(15)
	v_pk_fma_f32 v[166:167], v[166:167], s[92:93], v[50:51] op_sel_hi:[1,0,1]
	v_pk_fma_f32 v[164:165], v[164:165], s[92:93], v[48:49] op_sel_hi:[1,0,1]
	global_store_dwordx4 v[228:229], v[164:167], off
	s_waitcnt vmcnt(15)
	v_pk_fma_f32 v[168:169], v[168:169], s[92:93], v[52:53] op_sel_hi:[1,0,1]
	v_pk_fma_f32 v[170:171], v[170:171], s[92:93], v[54:55] op_sel_hi:[1,0,1]
	global_store_dwordx4 v[228:229], v[168:171], off offset:32
	s_waitcnt vmcnt(15)
	v_pk_fma_f32 v[172:173], v[172:173], s[92:93], v[56:57] op_sel_hi:[1,0,1]
	v_pk_fma_f32 v[174:175], v[174:175], s[92:93], v[58:59] op_sel_hi:[1,0,1]
	global_store_dwordx4 v[228:229], v[172:175], off offset:64
	s_waitcnt vmcnt(15)
	v_pk_fma_f32 v[176:177], v[176:177], s[92:93], v[60:61] op_sel_hi:[1,0,1]
	v_pk_fma_f32 v[178:179], v[178:179], s[92:93], v[62:63] op_sel_hi:[1,0,1]
	global_store_dwordx4 v[228:229], v[176:179], off offset:96
	s_waitcnt vmcnt(15)
	v_pk_fma_f32 v[182:183], v[182:183], s[92:93], v[34:35] op_sel_hi:[1,0,1]
	v_pk_fma_f32 v[180:181], v[180:181], s[92:93], v[32:33] op_sel_hi:[1,0,1]
	global_store_dwordx4 v[228:229], v[180:183], off offset:128
	s_waitcnt vmcnt(15)
	v_pk_fma_f32 v[184:185], v[184:185], s[92:93], v[36:37] op_sel_hi:[1,0,1]
	v_pk_fma_f32 v[186:187], v[186:187], s[92:93], v[38:39] op_sel_hi:[1,0,1]
	global_store_dwordx4 v[228:229], v[184:187], off offset:160
	s_waitcnt vmcnt(15)
	v_pk_fma_f32 v[188:189], v[188:189], s[92:93], v[40:41] op_sel_hi:[1,0,1]
	v_pk_fma_f32 v[190:191], v[190:191], s[92:93], v[42:43] op_sel_hi:[1,0,1]
	global_store_dwordx4 v[228:229], v[188:191], off offset:192
	s_waitcnt vmcnt(15)
	v_pk_fma_f32 v[192:193], v[192:193], s[92:93], v[44:45] op_sel_hi:[1,0,1]
	v_pk_fma_f32 v[194:195], v[194:195], s[92:93], v[46:47] op_sel_hi:[1,0,1]
	global_store_dwordx4 v[228:229], v[192:195], off offset:224
	s_waitcnt vmcnt(15)
	v_pk_fma_f32 v[198:199], v[198:199], s[92:93], v[18:19] op_sel_hi:[1,0,1]
	v_pk_fma_f32 v[196:197], v[196:197], s[92:93], v[16:17] op_sel_hi:[1,0,1]
	global_store_dwordx4 v[232:233], v[196:199], off
	s_waitcnt vmcnt(15)
	v_pk_fma_f32 v[200:201], v[200:201], s[92:93], v[20:21] op_sel_hi:[1,0,1]
	v_pk_fma_f32 v[202:203], v[202:203], s[92:93], v[22:23] op_sel_hi:[1,0,1]
	global_store_dwordx4 v[232:233], v[200:203], off offset:32
	s_waitcnt vmcnt(15)
	v_pk_fma_f32 v[204:205], v[204:205], s[92:93], v[24:25] op_sel_hi:[1,0,1]
	v_pk_fma_f32 v[206:207], v[206:207], s[92:93], v[26:27] op_sel_hi:[1,0,1]
	global_store_dwordx4 v[232:233], v[204:207], off offset:64
	s_waitcnt vmcnt(15)
	v_pk_fma_f32 v[208:209], v[208:209], s[92:93], v[28:29] op_sel_hi:[1,0,1]
	v_pk_fma_f32 v[210:211], v[210:211], s[92:93], v[30:31] op_sel_hi:[1,0,1]
	global_store_dwordx4 v[232:233], v[208:211], off offset:96
	s_waitcnt vmcnt(15)
	v_pk_fma_f32 v[214:215], v[214:215], s[92:93], v[2:3] op_sel_hi:[1,0,1]
	v_pk_fma_f32 v[212:213], v[212:213], s[92:93], v[0:1] op_sel_hi:[1,0,1]
	global_store_dwordx4 v[232:233], v[212:215], off offset:128
	s_waitcnt vmcnt(15)
	v_pk_fma_f32 v[216:217], v[216:217], s[92:93], v[4:5] op_sel_hi:[1,0,1]
	v_pk_fma_f32 v[218:219], v[218:219], s[92:93], v[6:7] op_sel_hi:[1,0,1]
	global_store_dwordx4 v[232:233], v[216:219], off offset:160
	s_waitcnt vmcnt(15)
	v_pk_fma_f32 v[220:221], v[220:221], s[92:93], v[8:9] op_sel_hi:[1,0,1]
	v_pk_fma_f32 v[222:223], v[222:223], s[92:93], v[10:11] op_sel_hi:[1,0,1]
	global_store_dwordx4 v[232:233], v[220:223], off offset:192
	s_waitcnt vmcnt(15)
	v_pk_fma_f32 v[224:225], v[224:225], s[92:93], v[12:13] op_sel_hi:[1,0,1]
	v_pk_fma_f32 v[226:227], v[226:227], s[92:93], v[14:15] op_sel_hi:[1,0,1]
	global_store_dwordx4 v[232:233], v[224:227], off offset:224
	s_cmpk_lt_i32 s14, 0x400
	s_cbranch_scc0 .LBB0_255

.LBB0_561:
	s_lshl_b32 s80, s28, 7
	v_readlane_b32 s44, v245, 59
	s_ashr_i32 s81, s80, 31
	v_readlane_b32 s45, v245, 60
	s_lshl_b32 s82, s29, 7
	s_lshl_b64 s[28:29], s[80:81], 11
	v_readlane_b32 s46, v245, 61
	v_readlane_b32 s47, v245, 62
	v_readlane_b32 s48, v245, 63
	v_readlane_b32 s49, v244, 0
	s_mov_b64 s[36:37], s[44:45]
	v_readlane_b32 s52, v244, 3
	v_readlane_b32 s53, v244, 4
	v_readlane_b32 s54, v244, 5
	v_readlane_b32 s55, v244, 6
	v_readlane_b32 s56, v244, 7
	v_readlane_b32 s57, v244, 8
	v_readlane_b32 s58, v244, 9
	v_readlane_b32 s59, v244, 10
	s_add_u32 s34, s36, s28
	s_addc_u32 s35, s37, s29
	s_ashr_i32 s83, s82, 31
	v_readlane_b32 s52, v245, 37
	s_lshl_b64 s[28:29], s[82:83], 11
	v_readlane_b32 s56, v245, 41
	v_readlane_b32 s57, v245, 42
	s_add_u32 s70, s56, s28
	s_addc_u32 s71, s57, s29
	v_readfirstlane_b32 s29, v88
	v_mov_b32_e32 v2, s71
	v_mov_b32_e32 v3, s35
	v_mov_b32_e32 v4, s70
	v_mov_b32_e32 v5, s34
	s_add_u32 s98, s34, 0x80
	s_addc_u32 s99, s35, 0
	v_lshl_add_u64 v[72:73], s[34:35], 0, v[64:65]
	s_mov_b32 m0, s29
	v_cndmask_b32_e64 v1, v2, v3, s[4:5]
	v_cndmask_b32_e64 v0, v4, v5, s[4:5]
	v_readfirstlane_b32 s84, v91
	global_load_lds_dwordx4 v[72:73], off
	v_lshl_add_u64 v[74:75], v[0:1], 0, v[66:67]
	s_mov_b32 m0, s84
	v_cndmask_b32_e64 v1, v2, v3, s[6:7]
	v_cndmask_b32_e64 v0, v4, v5, s[6:7]
	v_readfirstlane_b32 s85, v92
	global_load_lds_dwordx4 v[74:75], off
	v_lshl_add_u64 v[76:77], v[0:1], 0, v[68:69]
	s_mov_b32 m0, s85
	v_cndmask_b32_e64 v1, v2, v3, s[8:9]
	v_cndmask_b32_e64 v0, v4, v5, s[8:9]
	v_readfirstlane_b32 s86, v93
	global_load_lds_dwordx4 v[76:77], off
	v_lshl_add_u64 v[78:79], v[0:1], 0, v[70:71]
	s_mov_b32 m0, s86
	v_readfirstlane_b32 s87, v94
	global_load_lds_dwordx4 v[78:79], off
	s_add_u32 s100, s70, 0x80
	s_addc_u32 s101, s71, 0
	v_lshl_add_u64 v[80:81], s[70:71], 0, v[64:65]
	s_mov_b32 m0, s87
	v_readfirstlane_b32 s89, v95
	global_load_lds_dwordx4 v[80:81], off
	v_lshl_add_u64 v[82:83], s[70:71], 0, v[66:67]
	s_mov_b32 m0, s89
	v_readfirstlane_b32 s90, v96
	global_load_lds_dwordx4 v[82:83], off
	v_lshl_add_u64 v[84:85], s[70:71], 0, v[68:69]
	s_mov_b32 m0, s90
	v_readfirstlane_b32 s91, v97
	global_load_lds_dwordx4 v[84:85], off
	v_lshl_add_u64 v[86:87], s[70:71], 0, v[70:71]
	s_mov_b32 m0, s91
	v_readfirstlane_b32 s70, v98
	global_load_lds_dwordx4 v[86:87], off
	s_mov_b32 m0, s70
	v_readfirstlane_b32 s71, v99
	s_waitcnt vmcnt(0)
	s_waitcnt vmcnt(0) lgkmcnt(0)
	s_barrier
	global_load_lds_dwordx4 v64, s[98:99]
	s_mov_b32 m0, s71
	v_readfirstlane_b32 s72, v100
	global_load_lds_dwordx4 v66, s[98:99]
	s_mov_b32 m0, s72
	v_readfirstlane_b32 s73, v101
	global_load_lds_dwordx4 v68, s[98:99]
	s_mov_b32 m0, s73
	v_readfirstlane_b32 s81, v102
	global_load_lds_dwordx4 v70, s[98:99]
	s_mov_b32 m0, s81
	v_readfirstlane_b32 s83, v103
	global_load_lds_dwordx4 v64, s[100:101]
	s_mov_b32 m0, s83
	v_readfirstlane_b32 s88, v104
	global_load_lds_dwordx4 v66, s[100:101]
	s_mov_b32 m0, s88
	v_readfirstlane_b32 s28, v105
	global_load_lds_dwordx4 v68, s[100:101]
	s_mov_b32 m0, s28
	v_readfirstlane_b32 s34, v92
	global_load_lds_dwordx4 v70, s[100:101]
	s_add_u32 s98, s98, 0x80
	s_addc_u32 s99, s99, 0
	s_add_u32 s100, s100, 0x80
	s_addc_u32 s101, s101, 0
	ds_read_b128 v[0:3], v106
	ds_read_b128 v[4:7], v107 offset:16384
	ds_read_b128 v[8:11], v106 offset:4096
	ds_read_b128 v[12:15], v107 offset:20480
	s_waitcnt lgkmcnt(0)
	v_mfma_f32_32x32x16_bf16 v[48:63], v[4:7], v[0:3], 0
	ds_read_b128 v[114:117], v108
	ds_read_b128 v[118:121], v109 offset:16384
	ds_read_b128 v[122:125], v108 offset:4096
	ds_read_b128 v[126:129], v109 offset:20480
	s_mov_b32 m0, s29
	v_readfirstlane_b32 s35, v93
	s_mov_b64 s[40:41], s[48:49]
	v_add_u32_e32 v236, s80, v89
	v_or_b32_e32 v240, s82, v90
	v_ashrrev_i32_e32 v237, 31, v236
	v_ashrrev_i32_e32 v241, 31, v240
	v_or_b32_e32 v234, 32, v236
	v_lshlrev_b64 v[238:239], 12, v[236:237]
	v_lshlrev_b64 v[240:241], 2, v[240:241]
	v_ashrrev_i32_e32 v235, 31, v234
	v_lshlrev_b64 v[234:235], 12, v[234:235]
	v_lshl_add_u64 v[242:243], s[40:41], 0, v[238:239]
	v_lshl_add_u64 v[230:231], s[40:41], 0, v[234:235]
	v_lshl_add_u64 v[242:243], v[242:243], 0, v[240:241]
	v_lshl_add_u64 v[230:231], v[230:231], 0, v[240:241]
	global_load_dwordx4 v[164:167], v[242:243], off
	global_load_dwordx4 v[168:171], v[242:243], off offset:32
	global_load_dwordx4 v[172:175], v[242:243], off offset:64
	global_load_dwordx4 v[176:179], v[242:243], off offset:96
	global_load_dwordx4 v[180:183], v[242:243], off offset:128
	global_load_dwordx4 v[184:187], v[242:243], off offset:160
	global_load_dwordx4 v[188:191], v[242:243], off offset:192
	global_load_dwordx4 v[192:195], v[242:243], off offset:224
	global_load_dwordx4 v[196:199], v[230:231], off
	global_load_dwordx4 v[200:203], v[230:231], off offset:32
	global_load_dwordx4 v[204:207], v[230:231], off offset:64
	global_load_dwordx4 v[208:211], v[230:231], off offset:96
	global_load_dwordx4 v[212:215], v[230:231], off offset:128
	global_load_dwordx4 v[216:219], v[230:231], off offset:160
	global_load_dwordx4 v[220:223], v[230:231], off offset:192
	global_load_dwordx4 v[224:227], v[230:231], off offset:224
	s_mov_b64 s[38:39], s[46:47]
	v_readlane_b32 s50, v244, 1
	v_readlane_b32 s51, v244, 2
	v_mfma_f32_32x32x16_bf16 v[32:47], v[12:15], v[0:3], 0
	v_readlane_b32 s53, v245, 38
	v_readlane_b32 s54, v245, 39
	v_readlane_b32 s55, v245, 40
	v_readlane_b32 s58, v245, 43
	v_readlane_b32 s59, v245, 44
	v_readlane_b32 s60, v245, 45
	v_readlane_b32 s61, v245, 46
	v_mfma_f32_32x32x16_bf16 v[16:31], v[4:7], v[8:11], 0
	v_readlane_b32 s62, v245, 47
	v_readlane_b32 s63, v245, 48
	v_readlane_b32 s64, v245, 49
	v_readlane_b32 s65, v245, 50
	v_readlane_b32 s66, v245, 51
	v_readlane_b32 s67, v245, 52
	v_mfma_f32_32x32x16_bf16 v[0:15], v[12:15], v[8:11], 0
	s_waitcnt lgkmcnt(0)
	v_mfma_f32_32x32x16_bf16 v[48:63], v[118:121], v[114:117], v[48:63]
	v_mfma_f32_32x32x16_bf16 v[32:47], v[126:129], v[114:117], v[32:47]
	v_mfma_f32_32x32x16_bf16 v[16:31], v[118:121], v[122:125], v[16:31]
	v_mfma_f32_32x32x16_bf16 v[0:15], v[126:129], v[122:125], v[0:15]
	ds_read_b128 v[114:117], v110
	ds_read_b128 v[118:121], v111 offset:16384
	ds_read_b128 v[122:125], v110 offset:4096
	ds_read_b128 v[126:129], v111 offset:20480
	s_waitcnt lgkmcnt(0)
	v_mfma_f32_32x32x16_bf16 v[48:63], v[118:121], v[114:117], v[48:63]
	v_mfma_f32_32x32x16_bf16 v[32:47], v[126:129], v[114:117], v[32:47]
	v_mfma_f32_32x32x16_bf16 v[16:31], v[118:121], v[122:125], v[16:31]
	v_mfma_f32_32x32x16_bf16 v[0:15], v[126:129], v[122:125], v[0:15]
	ds_read_b128 v[114:117], v112
	ds_read_b128 v[118:121], v113 offset:16384
	ds_read_b128 v[122:125], v112 offset:4096
	ds_read_b128 v[126:129], v113 offset:20480
	s_waitcnt vmcnt(0)
	s_waitcnt vmcnt(0) lgkmcnt(0)
	s_barrier
	v_mfma_f32_32x32x16_bf16 v[48:63], v[118:121], v[114:117], v[48:63]
	v_mfma_f32_32x32x16_bf16 v[32:47], v[126:129], v[114:117], v[32:47]
	global_load_lds_dwordx4 v64, s[98:99]
	s_mov_b32 m0, s84
	s_nop 0
	global_load_lds_dwordx4 v66, s[98:99]
	s_mov_b32 m0, s85
	v_mfma_f32_32x32x16_bf16 v[16:31], v[118:121], v[122:125], v[16:31]
	global_load_lds_dwordx4 v68, s[98:99]
	s_mov_b32 m0, s86
	s_nop 0
	global_load_lds_dwordx4 v70, s[98:99]
	s_mov_b32 m0, s87
	v_mfma_f32_32x32x16_bf16 v[0:15], v[126:129], v[122:125], v[0:15]
	global_load_lds_dwordx4 v64, s[100:101]
	s_mov_b32 m0, s89
	s_nop 0
	global_load_lds_dwordx4 v66, s[100:101]
	s_mov_b32 m0, s90
	s_nop 0
	global_load_lds_dwordx4 v68, s[100:101]
	s_mov_b32 m0, s91
	s_nop 0
	global_load_lds_dwordx4 v70, s[100:101]
	s_add_u32 s98, s98, 0x80
	s_addc_u32 s99, s99, 0
	s_add_u32 s100, s100, 0x80
	s_addc_u32 s101, s101, 0
	ds_read_b128 v[114:117], v106 offset:32768
	ds_read_b128 v[118:121], v107 offset:49152
	ds_read_b128 v[122:125], v106 offset:36864
	ds_read_b128 v[126:129], v107 offset:53248
	s_waitcnt lgkmcnt(0)
	v_mfma_f32_32x32x16_bf16 v[48:63], v[118:121], v[114:117], v[48:63]
	s_mov_b32 m0, s70
	v_mfma_f32_32x32x16_bf16 v[32:47], v[126:129], v[114:117], v[32:47]
	v_mfma_f32_32x32x16_bf16 v[16:31], v[118:121], v[122:125], v[16:31]
	v_mfma_f32_32x32x16_bf16 v[0:15], v[126:129], v[122:125], v[0:15]
	ds_read_b128 v[114:117], v108 offset:32768
	ds_read_b128 v[118:121], v109 offset:49152
	ds_read_b128 v[122:125], v108 offset:36864
	ds_read_b128 v[126:129], v109 offset:53248
	s_waitcnt lgkmcnt(0)
	v_mfma_f32_32x32x16_bf16 v[48:63], v[118:121], v[114:117], v[48:63]
	v_mfma_f32_32x32x16_bf16 v[32:47], v[126:129], v[114:117], v[32:47]
	v_mfma_f32_32x32x16_bf16 v[16:31], v[118:121], v[122:125], v[16:31]
	v_mfma_f32_32x32x16_bf16 v[0:15], v[126:129], v[122:125], v[0:15]
	ds_read_b128 v[114:117], v110 offset:32768
	ds_read_b128 v[118:121], v111 offset:49152
	ds_read_b128 v[122:125], v110 offset:36864
	ds_read_b128 v[126:129], v111 offset:53248
	s_waitcnt lgkmcnt(0)
	v_mfma_f32_32x32x16_bf16 v[48:63], v[118:121], v[114:117], v[48:63]
	v_mfma_f32_32x32x16_bf16 v[32:47], v[126:129], v[114:117], v[32:47]
	v_mfma_f32_32x32x16_bf16 v[16:31], v[118:121], v[122:125], v[16:31]
	v_mfma_f32_32x32x16_bf16 v[0:15], v[126:129], v[122:125], v[0:15]
	ds_read_b128 v[114:117], v112 offset:32768
	ds_read_b128 v[118:121], v113 offset:49152
	ds_read_b128 v[122:125], v112 offset:36864
	ds_read_b128 v[126:129], v113 offset:53248
	s_waitcnt vmcnt(0)
	s_waitcnt vmcnt(0) lgkmcnt(0)
	s_barrier
	v_mfma_f32_32x32x16_bf16 v[48:63], v[118:121], v[114:117], v[48:63]
	v_mfma_f32_32x32x16_bf16 v[32:47], v[126:129], v[114:117], v[32:47]
	global_load_lds_dwordx4 v64, s[98:99]
	s_mov_b32 m0, s71
	s_nop 0
	global_load_lds_dwordx4 v66, s[98:99]
	s_mov_b32 m0, s72
	v_mfma_f32_32x32x16_bf16 v[16:31], v[118:121], v[122:125], v[16:31]
	global_load_lds_dwordx4 v68, s[98:99]
	s_mov_b32 m0, s73
	s_nop 0
	global_load_lds_dwordx4 v70, s[98:99]
	s_mov_b32 m0, s81
	v_mfma_f32_32x32x16_bf16 v[0:15], v[126:129], v[122:125], v[0:15]
	global_load_lds_dwordx4 v64, s[100:101]
	s_mov_b32 m0, s83
	s_nop 0
	global_load_lds_dwordx4 v66, s[100:101]
	s_mov_b32 m0, s88
	s_nop 0
	global_load_lds_dwordx4 v68, s[100:101]
	s_mov_b32 m0, s28
	s_nop 0
	global_load_lds_dwordx4 v70, s[100:101]
	s_add_u32 s98, s98, 0x80
	s_addc_u32 s99, s99, 0
	s_add_u32 s100, s100, 0x80
	s_addc_u32 s101, s101, 0
	ds_read_b128 v[114:117], v106
	ds_read_b128 v[118:121], v107 offset:16384
	ds_read_b128 v[122:125], v106 offset:4096
	ds_read_b128 v[126:129], v107 offset:20480
	s_waitcnt lgkmcnt(0)
	v_mfma_f32_32x32x16_bf16 v[48:63], v[118:121], v[114:117], v[48:63]
	s_mov_b32 m0, s29
	v_mfma_f32_32x32x16_bf16 v[32:47], v[126:129], v[114:117], v[32:47]
	v_mfma_f32_32x32x16_bf16 v[16:31], v[118:121], v[122:125], v[16:31]
	v_mfma_f32_32x32x16_bf16 v[0:15], v[126:129], v[122:125], v[0:15]
	ds_read_b128 v[114:117], v108
	ds_read_b128 v[118:121], v109 offset:16384
	ds_read_b128 v[122:125], v108 offset:4096
	ds_read_b128 v[126:129], v109 offset:20480
	s_waitcnt lgkmcnt(0)
	v_mfma_f32_32x32x16_bf16 v[48:63], v[118:121], v[114:117], v[48:63]
	v_mfma_f32_32x32x16_bf16 v[32:47], v[126:129], v[114:117], v[32:47]
	v_mfma_f32_32x32x16_bf16 v[16:31], v[118:121], v[122:125], v[16:31]
	v_mfma_f32_32x32x16_bf16 v[0:15], v[126:129], v[122:125], v[0:15]
	ds_read_b128 v[114:117], v110
	ds_read_b128 v[118:121], v111 offset:16384
	ds_read_b128 v[122:125], v110 offset:4096
	ds_read_b128 v[126:129], v111 offset:20480
	s_waitcnt lgkmcnt(0)
	v_mfma_f32_32x32x16_bf16 v[48:63], v[118:121], v[114:117], v[48:63]
	v_mfma_f32_32x32x16_bf16 v[32:47], v[126:129], v[114:117], v[32:47]
	v_mfma_f32_32x32x16_bf16 v[16:31], v[118:121], v[122:125], v[16:31]
	v_mfma_f32_32x32x16_bf16 v[0:15], v[126:129], v[122:125], v[0:15]
	ds_read_b128 v[114:117], v112
	ds_read_b128 v[118:121], v113 offset:16384
	ds_read_b128 v[122:125], v112 offset:4096
	ds_read_b128 v[126:129], v113 offset:20480
	s_waitcnt vmcnt(0)
	s_waitcnt vmcnt(0) lgkmcnt(0)
	s_barrier
	v_mfma_f32_32x32x16_bf16 v[48:63], v[118:121], v[114:117], v[48:63]
	v_mfma_f32_32x32x16_bf16 v[32:47], v[126:129], v[114:117], v[32:47]
	global_load_lds_dwordx4 v64, s[98:99]
	s_mov_b32 m0, s84
	s_nop 0
	global_load_lds_dwordx4 v66, s[98:99]
	s_mov_b32 m0, s85
	v_mfma_f32_32x32x16_bf16 v[16:31], v[118:121], v[122:125], v[16:31]
	global_load_lds_dwordx4 v68, s[98:99]
	s_mov_b32 m0, s86
	s_nop 0
	global_load_lds_dwordx4 v70, s[98:99]
	s_mov_b32 m0, s87
	v_mfma_f32_32x32x16_bf16 v[0:15], v[126:129], v[122:125], v[0:15]
	global_load_lds_dwordx4 v64, s[100:101]
	s_mov_b32 m0, s89
	s_nop 0
	global_load_lds_dwordx4 v66, s[100:101]
	s_mov_b32 m0, s90
	s_nop 0
	global_load_lds_dwordx4 v68, s[100:101]
	s_mov_b32 m0, s91
	s_nop 0
	global_load_lds_dwordx4 v70, s[100:101]
	s_add_u32 s98, s98, 0x80
	s_addc_u32 s99, s99, 0
	s_add_u32 s100, s100, 0x80
	s_addc_u32 s101, s101, 0
	ds_read_b128 v[114:117], v106 offset:32768
	ds_read_b128 v[118:121], v107 offset:49152
	ds_read_b128 v[122:125], v106 offset:36864
	ds_read_b128 v[126:129], v107 offset:53248
	s_waitcnt lgkmcnt(0)
	v_mfma_f32_32x32x16_bf16 v[48:63], v[118:121], v[114:117], v[48:63]
	s_mov_b32 m0, s70
	v_mfma_f32_32x32x16_bf16 v[32:47], v[126:129], v[114:117], v[32:47]
	v_mfma_f32_32x32x16_bf16 v[16:31], v[118:121], v[122:125], v[16:31]
	v_mfma_f32_32x32x16_bf16 v[0:15], v[126:129], v[122:125], v[0:15]
	ds_read_b128 v[114:117], v108 offset:32768
	ds_read_b128 v[118:121], v109 offset:49152
	ds_read_b128 v[122:125], v108 offset:36864
	ds_read_b128 v[126:129], v109 offset:53248
	s_waitcnt lgkmcnt(0)
	v_mfma_f32_32x32x16_bf16 v[48:63], v[118:121], v[114:117], v[48:63]
	v_mfma_f32_32x32x16_bf16 v[32:47], v[126:129], v[114:117], v[32:47]
	v_mfma_f32_32x32x16_bf16 v[16:31], v[118:121], v[122:125], v[16:31]
	v_mfma_f32_32x32x16_bf16 v[0:15], v[126:129], v[122:125], v[0:15]
	ds_read_b128 v[114:117], v110 offset:32768
	ds_read_b128 v[118:121], v111 offset:49152
	ds_read_b128 v[122:125], v110 offset:36864
	ds_read_b128 v[126:129], v111 offset:53248
	s_waitcnt lgkmcnt(0)
	v_mfma_f32_32x32x16_bf16 v[48:63], v[118:121], v[114:117], v[48:63]
	v_mfma_f32_32x32x16_bf16 v[32:47], v[126:129], v[114:117], v[32:47]
	v_mfma_f32_32x32x16_bf16 v[16:31], v[118:121], v[122:125], v[16:31]
	v_mfma_f32_32x32x16_bf16 v[0:15], v[126:129], v[122:125], v[0:15]
	ds_read_b128 v[114:117], v112 offset:32768
	ds_read_b128 v[118:121], v113 offset:49152
	ds_read_b128 v[122:125], v112 offset:36864
	ds_read_b128 v[126:129], v113 offset:53248
	s_waitcnt vmcnt(0)
	s_waitcnt vmcnt(0) lgkmcnt(0)
	s_barrier
	v_mfma_f32_32x32x16_bf16 v[48:63], v[118:121], v[114:117], v[48:63]
	v_mfma_f32_32x32x16_bf16 v[32:47], v[126:129], v[114:117], v[32:47]
	global_load_lds_dwordx4 v64, s[98:99]
	s_mov_b32 m0, s71
	s_nop 0
	global_load_lds_dwordx4 v66, s[98:99]
	s_mov_b32 m0, s72
	v_mfma_f32_32x32x16_bf16 v[16:31], v[118:121], v[122:125], v[16:31]
	global_load_lds_dwordx4 v68, s[98:99]
	s_mov_b32 m0, s73
	s_nop 0
	global_load_lds_dwordx4 v70, s[98:99]
	s_mov_b32 m0, s81
	v_mfma_f32_32x32x16_bf16 v[0:15], v[126:129], v[122:125], v[0:15]
	global_load_lds_dwordx4 v64, s[100:101]
	s_mov_b32 m0, s83
	s_nop 0
	global_load_lds_dwordx4 v66, s[100:101]
	s_mov_b32 m0, s88
	s_nop 0
	global_load_lds_dwordx4 v68, s[100:101]
	s_mov_b32 m0, s28
	s_nop 0
	global_load_lds_dwordx4 v70, s[100:101]
	s_add_u32 s98, s98, 0x80
	s_addc_u32 s99, s99, 0
	s_add_u32 s100, s100, 0x80
	s_addc_u32 s101, s101, 0
	ds_read_b128 v[114:117], v106
	ds_read_b128 v[118:121], v107 offset:16384
	ds_read_b128 v[122:125], v106 offset:4096
	ds_read_b128 v[126:129], v107 offset:20480
	s_waitcnt lgkmcnt(0)
	v_mfma_f32_32x32x16_bf16 v[48:63], v[118:121], v[114:117], v[48:63]
	s_mov_b32 m0, s29
	v_mfma_f32_32x32x16_bf16 v[32:47], v[126:129], v[114:117], v[32:47]
	v_mfma_f32_32x32x16_bf16 v[16:31], v[118:121], v[122:125], v[16:31]
	v_mfma_f32_32x32x16_bf16 v[0:15], v[126:129], v[122:125], v[0:15]
	ds_read_b128 v[114:117], v108
	ds_read_b128 v[118:121], v109 offset:16384
	ds_read_b128 v[122:125], v108 offset:4096
	ds_read_b128 v[126:129], v109 offset:20480
	s_waitcnt lgkmcnt(0)
	v_mfma_f32_32x32x16_bf16 v[48:63], v[118:121], v[114:117], v[48:63]
	v_mfma_f32_32x32x16_bf16 v[32:47], v[126:129], v[114:117], v[32:47]
	v_mfma_f32_32x32x16_bf16 v[16:31], v[118:121], v[122:125], v[16:31]
	v_mfma_f32_32x32x16_bf16 v[0:15], v[126:129], v[122:125], v[0:15]
	ds_read_b128 v[114:117], v110
	ds_read_b128 v[118:121], v111 offset:16384
	ds_read_b128 v[122:125], v110 offset:4096
	ds_read_b128 v[126:129], v111 offset:20480
	s_waitcnt lgkmcnt(0)
	v_mfma_f32_32x32x16_bf16 v[48:63], v[118:121], v[114:117], v[48:63]
	v_mfma_f32_32x32x16_bf16 v[32:47], v[126:129], v[114:117], v[32:47]
	v_mfma_f32_32x32x16_bf16 v[16:31], v[118:121], v[122:125], v[16:31]
	v_mfma_f32_32x32x16_bf16 v[0:15], v[126:129], v[122:125], v[0:15]
	ds_read_b128 v[114:117], v112
	ds_read_b128 v[118:121], v113 offset:16384
	ds_read_b128 v[122:125], v112 offset:4096
	ds_read_b128 v[126:129], v113 offset:20480
	s_waitcnt vmcnt(0)
	s_waitcnt vmcnt(0) lgkmcnt(0)
	s_barrier
	v_mfma_f32_32x32x16_bf16 v[48:63], v[118:121], v[114:117], v[48:63]
	v_mfma_f32_32x32x16_bf16 v[32:47], v[126:129], v[114:117], v[32:47]
	global_load_lds_dwordx4 v64, s[98:99]
	s_mov_b32 m0, s84
	s_nop 0
	global_load_lds_dwordx4 v66, s[98:99]
	s_mov_b32 m0, s85
	v_mfma_f32_32x32x16_bf16 v[16:31], v[118:121], v[122:125], v[16:31]
	global_load_lds_dwordx4 v68, s[98:99]
	s_mov_b32 m0, s86
	s_nop 0
	global_load_lds_dwordx4 v70, s[98:99]
	s_mov_b32 m0, s87
	v_mfma_f32_32x32x16_bf16 v[0:15], v[126:129], v[122:125], v[0:15]
	global_load_lds_dwordx4 v64, s[100:101]
	s_mov_b32 m0, s89
	s_nop 0
	global_load_lds_dwordx4 v66, s[100:101]
	s_mov_b32 m0, s90
	s_nop 0
	global_load_lds_dwordx4 v68, s[100:101]
	s_mov_b32 m0, s91
	s_nop 0
	global_load_lds_dwordx4 v70, s[100:101]
	s_add_u32 s98, s98, 0x80
	s_addc_u32 s99, s99, 0
	s_add_u32 s100, s100, 0x80
	s_addc_u32 s101, s101, 0
	ds_read_b128 v[114:117], v106 offset:32768
	ds_read_b128 v[118:121], v107 offset:49152
	ds_read_b128 v[122:125], v106 offset:36864
	ds_read_b128 v[126:129], v107 offset:53248
	s_waitcnt lgkmcnt(0)
	v_mfma_f32_32x32x16_bf16 v[48:63], v[118:121], v[114:117], v[48:63]
	s_mov_b32 m0, s70
	v_mfma_f32_32x32x16_bf16 v[32:47], v[126:129], v[114:117], v[32:47]
	v_mfma_f32_32x32x16_bf16 v[16:31], v[118:121], v[122:125], v[16:31]
	v_mfma_f32_32x32x16_bf16 v[0:15], v[126:129], v[122:125], v[0:15]
	ds_read_b128 v[114:117], v108 offset:32768
	ds_read_b128 v[118:121], v109 offset:49152
	ds_read_b128 v[122:125], v108 offset:36864
	ds_read_b128 v[126:129], v109 offset:53248
	s_waitcnt lgkmcnt(0)
	v_mfma_f32_32x32x16_bf16 v[48:63], v[118:121], v[114:117], v[48:63]
	v_mfma_f32_32x32x16_bf16 v[32:47], v[126:129], v[114:117], v[32:47]
	v_mfma_f32_32x32x16_bf16 v[16:31], v[118:121], v[122:125], v[16:31]
	v_mfma_f32_32x32x16_bf16 v[0:15], v[126:129], v[122:125], v[0:15]
	ds_read_b128 v[114:117], v110 offset:32768
	ds_read_b128 v[118:121], v111 offset:49152
	ds_read_b128 v[122:125], v110 offset:36864
	ds_read_b128 v[126:129], v111 offset:53248
	s_waitcnt lgkmcnt(0)
	v_mfma_f32_32x32x16_bf16 v[48:63], v[118:121], v[114:117], v[48:63]
	v_mfma_f32_32x32x16_bf16 v[32:47], v[126:129], v[114:117], v[32:47]
	v_mfma_f32_32x32x16_bf16 v[16:31], v[118:121], v[122:125], v[16:31]
	v_mfma_f32_32x32x16_bf16 v[0:15], v[126:129], v[122:125], v[0:15]
	ds_read_b128 v[114:117], v112 offset:32768
	ds_read_b128 v[118:121], v113 offset:49152
	ds_read_b128 v[122:125], v112 offset:36864
	ds_read_b128 v[126:129], v113 offset:53248
	s_waitcnt vmcnt(0)
	s_waitcnt vmcnt(0) lgkmcnt(0)
	s_barrier
	v_mfma_f32_32x32x16_bf16 v[48:63], v[118:121], v[114:117], v[48:63]
	v_mfma_f32_32x32x16_bf16 v[32:47], v[126:129], v[114:117], v[32:47]
	global_load_lds_dwordx4 v64, s[98:99]
	s_mov_b32 m0, s71
	s_nop 0
	global_load_lds_dwordx4 v66, s[98:99]
	s_mov_b32 m0, s72
	v_mfma_f32_32x32x16_bf16 v[16:31], v[118:121], v[122:125], v[16:31]
	global_load_lds_dwordx4 v68, s[98:99]
	s_mov_b32 m0, s73
	s_nop 0
	global_load_lds_dwordx4 v70, s[98:99]
	s_mov_b32 m0, s81
	v_mfma_f32_32x32x16_bf16 v[0:15], v[126:129], v[122:125], v[0:15]
	global_load_lds_dwordx4 v64, s[100:101]
	s_mov_b32 m0, s83
	s_nop 0
	global_load_lds_dwordx4 v66, s[100:101]
	s_mov_b32 m0, s88
	s_nop 0
	global_load_lds_dwordx4 v68, s[100:101]
	s_mov_b32 m0, s28
	s_nop 0
	global_load_lds_dwordx4 v70, s[100:101]
	s_add_u32 s98, s98, 0x80
	s_addc_u32 s99, s99, 0
	s_add_u32 s100, s100, 0x80
	s_addc_u32 s101, s101, 0
	ds_read_b128 v[114:117], v106
	ds_read_b128 v[118:121], v107 offset:16384
	ds_read_b128 v[122:125], v106 offset:4096
	ds_read_b128 v[126:129], v107 offset:20480
	s_waitcnt lgkmcnt(0)
	v_mfma_f32_32x32x16_bf16 v[48:63], v[118:121], v[114:117], v[48:63]
	s_mov_b32 m0, s29
	v_readfirstlane_b32 s29, v91
	v_mfma_f32_32x32x16_bf16 v[32:47], v[126:129], v[114:117], v[32:47]
	v_mfma_f32_32x32x16_bf16 v[16:31], v[118:121], v[122:125], v[16:31]
	v_mfma_f32_32x32x16_bf16 v[0:15], v[126:129], v[122:125], v[0:15]
	ds_read_b128 v[114:117], v108
	ds_read_b128 v[118:121], v109 offset:16384
	ds_read_b128 v[122:125], v108 offset:4096
	ds_read_b128 v[126:129], v109 offset:20480
	s_waitcnt lgkmcnt(0)
	v_mfma_f32_32x32x16_bf16 v[48:63], v[118:121], v[114:117], v[48:63]
	v_mfma_f32_32x32x16_bf16 v[32:47], v[126:129], v[114:117], v[32:47]
	v_mfma_f32_32x32x16_bf16 v[16:31], v[118:121], v[122:125], v[16:31]
	v_mfma_f32_32x32x16_bf16 v[0:15], v[126:129], v[122:125], v[0:15]
	ds_read_b128 v[114:117], v110
	ds_read_b128 v[118:121], v111 offset:16384
	ds_read_b128 v[122:125], v110 offset:4096
	ds_read_b128 v[126:129], v111 offset:20480
	s_waitcnt lgkmcnt(0)
	v_mfma_f32_32x32x16_bf16 v[48:63], v[118:121], v[114:117], v[48:63]
	v_mfma_f32_32x32x16_bf16 v[32:47], v[126:129], v[114:117], v[32:47]
	v_mfma_f32_32x32x16_bf16 v[16:31], v[118:121], v[122:125], v[16:31]
	v_mfma_f32_32x32x16_bf16 v[0:15], v[126:129], v[122:125], v[0:15]
	ds_read_b128 v[114:117], v112
	ds_read_b128 v[118:121], v113 offset:16384
	ds_read_b128 v[122:125], v112 offset:4096
	ds_read_b128 v[126:129], v113 offset:20480
	s_waitcnt vmcnt(0)
	s_waitcnt vmcnt(0) lgkmcnt(0)
	s_barrier
	v_mfma_f32_32x32x16_bf16 v[48:63], v[118:121], v[114:117], v[48:63]
	v_mfma_f32_32x32x16_bf16 v[32:47], v[126:129], v[114:117], v[32:47]
	global_load_lds_dwordx4 v64, s[98:99]
	s_mov_b32 m0, s84
	v_readfirstlane_b32 s84, v100
	global_load_lds_dwordx4 v66, s[98:99]
	s_mov_b32 m0, s85
	v_mfma_f32_32x32x16_bf16 v[16:31], v[118:121], v[122:125], v[16:31]
	global_load_lds_dwordx4 v68, s[98:99]
	s_mov_b32 m0, s86
	v_readfirstlane_b32 s85, v101
	global_load_lds_dwordx4 v70, s[98:99]
	s_mov_b32 m0, s87
	v_mfma_f32_32x32x16_bf16 v[0:15], v[126:129], v[122:125], v[0:15]
	global_load_lds_dwordx4 v64, s[100:101]
	s_mov_b32 m0, s89
	v_readfirstlane_b32 s86, v102
	global_load_lds_dwordx4 v66, s[100:101]
	s_mov_b32 m0, s90
	v_readfirstlane_b32 s87, v103
	global_load_lds_dwordx4 v68, s[100:101]
	s_mov_b32 m0, s91
	v_readfirstlane_b32 s89, v105
	global_load_lds_dwordx4 v70, s[100:101]
	s_add_u32 s98, s98, 0x80
	s_addc_u32 s99, s99, 0
	s_add_u32 s100, s100, 0x80
	s_addc_u32 s101, s101, 0
	ds_read_b128 v[114:117], v106 offset:32768
	ds_read_b128 v[118:121], v107 offset:49152
	ds_read_b128 v[122:125], v106 offset:36864
	ds_read_b128 v[126:129], v107 offset:53248
	s_waitcnt lgkmcnt(0)
	v_mfma_f32_32x32x16_bf16 v[48:63], v[118:121], v[114:117], v[48:63]
	s_mov_b32 m0, s70
	v_readfirstlane_b32 s70, v94
	v_mfma_f32_32x32x16_bf16 v[32:47], v[126:129], v[114:117], v[32:47]
	v_mfma_f32_32x32x16_bf16 v[16:31], v[118:121], v[122:125], v[16:31]
	v_mfma_f32_32x32x16_bf16 v[0:15], v[126:129], v[122:125], v[0:15]
	ds_read_b128 v[114:117], v108 offset:32768
	ds_read_b128 v[118:121], v109 offset:49152
	ds_read_b128 v[122:125], v108 offset:36864
	ds_read_b128 v[126:129], v109 offset:53248
	s_waitcnt lgkmcnt(0)
	v_mfma_f32_32x32x16_bf16 v[48:63], v[118:121], v[114:117], v[48:63]
	v_mfma_f32_32x32x16_bf16 v[32:47], v[126:129], v[114:117], v[32:47]
	v_mfma_f32_32x32x16_bf16 v[16:31], v[118:121], v[122:125], v[16:31]
	v_mfma_f32_32x32x16_bf16 v[0:15], v[126:129], v[122:125], v[0:15]
	ds_read_b128 v[114:117], v110 offset:32768
	ds_read_b128 v[118:121], v111 offset:49152
	ds_read_b128 v[122:125], v110 offset:36864
	ds_read_b128 v[126:129], v111 offset:53248
	s_waitcnt lgkmcnt(0)
	v_mfma_f32_32x32x16_bf16 v[48:63], v[118:121], v[114:117], v[48:63]
	v_mfma_f32_32x32x16_bf16 v[32:47], v[126:129], v[114:117], v[32:47]
	v_mfma_f32_32x32x16_bf16 v[16:31], v[118:121], v[122:125], v[16:31]
	v_mfma_f32_32x32x16_bf16 v[0:15], v[126:129], v[122:125], v[0:15]
	ds_read_b128 v[114:117], v112 offset:32768
	ds_read_b128 v[118:121], v113 offset:49152
	ds_read_b128 v[122:125], v112 offset:36864
	ds_read_b128 v[126:129], v113 offset:53248
	s_waitcnt vmcnt(0)
	s_waitcnt vmcnt(0) lgkmcnt(0)
	s_barrier
	v_mfma_f32_32x32x16_bf16 v[48:63], v[118:121], v[114:117], v[48:63]
	v_mfma_f32_32x32x16_bf16 v[32:47], v[126:129], v[114:117], v[32:47]
	global_load_lds_dwordx4 v64, s[98:99]
	s_mov_b32 m0, s71
	v_readfirstlane_b32 s71, v95
	global_load_lds_dwordx4 v66, s[98:99]
	s_mov_b32 m0, s72
	v_mfma_f32_32x32x16_bf16 v[16:31], v[118:121], v[122:125], v[16:31]
	global_load_lds_dwordx4 v68, s[98:99]
	s_mov_b32 m0, s73
	v_readfirstlane_b32 s72, v96
	global_load_lds_dwordx4 v70, s[98:99]
	s_mov_b32 m0, s81
	v_mfma_f32_32x32x16_bf16 v[0:15], v[126:129], v[122:125], v[0:15]
	global_load_lds_dwordx4 v64, s[100:101]
	s_mov_b32 m0, s83
	v_readfirstlane_b32 s73, v97
	global_load_lds_dwordx4 v66, s[100:101]
	s_mov_b32 m0, s88
	v_readfirstlane_b32 s81, v98
	global_load_lds_dwordx4 v68, s[100:101]
	s_mov_b32 m0, s28
	v_readfirstlane_b32 s28, v88
	global_load_lds_dwordx4 v70, s[100:101]
	s_add_u32 s98, s98, 0x80
	s_addc_u32 s99, s99, 0
	s_add_u32 s100, s100, 0x80
	s_addc_u32 s101, s101, 0
	ds_read_b128 v[114:117], v106
	ds_read_b128 v[118:121], v107 offset:16384
	ds_read_b128 v[122:125], v106 offset:4096
	ds_read_b128 v[126:129], v107 offset:20480
	s_waitcnt lgkmcnt(0)
	v_mfma_f32_32x32x16_bf16 v[48:63], v[118:121], v[114:117], v[48:63]
	s_mov_b32 m0, s28
	v_readfirstlane_b32 s83, v99
	v_readfirstlane_b32 s88, v104
	v_mfma_f32_32x32x16_bf16 v[32:47], v[126:129], v[114:117], v[32:47]
	v_mfma_f32_32x32x16_bf16 v[16:31], v[118:121], v[122:125], v[16:31]
	v_mfma_f32_32x32x16_bf16 v[0:15], v[126:129], v[122:125], v[0:15]
	ds_read_b128 v[114:117], v108
	ds_read_b128 v[118:121], v109 offset:16384
	ds_read_b128 v[122:125], v108 offset:4096
	ds_read_b128 v[126:129], v109 offset:20480
	s_waitcnt lgkmcnt(0)
	v_mfma_f32_32x32x16_bf16 v[48:63], v[118:121], v[114:117], v[48:63]
	v_mfma_f32_32x32x16_bf16 v[32:47], v[126:129], v[114:117], v[32:47]
	v_mfma_f32_32x32x16_bf16 v[16:31], v[118:121], v[122:125], v[16:31]
	v_mfma_f32_32x32x16_bf16 v[0:15], v[126:129], v[122:125], v[0:15]
	ds_read_b128 v[114:117], v110
	ds_read_b128 v[118:121], v111 offset:16384
	ds_read_b128 v[122:125], v110 offset:4096
	ds_read_b128 v[126:129], v111 offset:20480
	s_waitcnt lgkmcnt(0)
	v_mfma_f32_32x32x16_bf16 v[48:63], v[118:121], v[114:117], v[48:63]
	v_mfma_f32_32x32x16_bf16 v[32:47], v[126:129], v[114:117], v[32:47]
	v_mfma_f32_32x32x16_bf16 v[16:31], v[118:121], v[122:125], v[16:31]
	v_mfma_f32_32x32x16_bf16 v[0:15], v[126:129], v[122:125], v[0:15]
	ds_read_b128 v[114:117], v112
	ds_read_b128 v[118:121], v113 offset:16384
	ds_read_b128 v[122:125], v112 offset:4096
	ds_read_b128 v[126:129], v113 offset:20480
	s_waitcnt vmcnt(0)
	s_waitcnt vmcnt(0) lgkmcnt(0)
	s_barrier
	v_mfma_f32_32x32x16_bf16 v[48:63], v[118:121], v[114:117], v[48:63]
	v_mfma_f32_32x32x16_bf16 v[32:47], v[126:129], v[114:117], v[32:47]
	global_load_lds_dwordx4 v64, s[98:99]
	s_mov_b32 m0, s29
	s_nop 0
	global_load_lds_dwordx4 v66, s[98:99]
	s_mov_b32 m0, s34
	v_mfma_f32_32x32x16_bf16 v[16:31], v[118:121], v[122:125], v[16:31]
	global_load_lds_dwordx4 v68, s[98:99]
	s_mov_b32 m0, s35
	s_nop 0
	global_load_lds_dwordx4 v70, s[98:99]
	s_mov_b32 m0, s70
	v_mfma_f32_32x32x16_bf16 v[0:15], v[126:129], v[122:125], v[0:15]
	global_load_lds_dwordx4 v64, s[100:101]
	s_mov_b32 m0, s71
	s_nop 0
	global_load_lds_dwordx4 v66, s[100:101]
	s_mov_b32 m0, s72
	s_nop 0
	global_load_lds_dwordx4 v68, s[100:101]
	s_mov_b32 m0, s73
	s_nop 0
	global_load_lds_dwordx4 v70, s[100:101]
	s_add_u32 s98, s98, 0x80
	s_addc_u32 s99, s99, 0
	s_add_u32 s100, s100, 0x80
	s_addc_u32 s101, s101, 0
	ds_read_b128 v[114:117], v106 offset:32768
	ds_read_b128 v[118:121], v107 offset:49152
	ds_read_b128 v[122:125], v106 offset:36864
	ds_read_b128 v[126:129], v107 offset:53248
	s_waitcnt lgkmcnt(0)
	v_mfma_f32_32x32x16_bf16 v[48:63], v[118:121], v[114:117], v[48:63]
	s_mov_b32 m0, s81
	v_mfma_f32_32x32x16_bf16 v[32:47], v[126:129], v[114:117], v[32:47]
	v_mfma_f32_32x32x16_bf16 v[16:31], v[118:121], v[122:125], v[16:31]
	v_mfma_f32_32x32x16_bf16 v[0:15], v[126:129], v[122:125], v[0:15]
	ds_read_b128 v[114:117], v108 offset:32768
	ds_read_b128 v[118:121], v109 offset:49152
	ds_read_b128 v[122:125], v108 offset:36864
	ds_read_b128 v[126:129], v109 offset:53248
	s_waitcnt lgkmcnt(0)
	v_mfma_f32_32x32x16_bf16 v[48:63], v[118:121], v[114:117], v[48:63]
	v_mfma_f32_32x32x16_bf16 v[32:47], v[126:129], v[114:117], v[32:47]
	v_mfma_f32_32x32x16_bf16 v[16:31], v[118:121], v[122:125], v[16:31]
	v_mfma_f32_32x32x16_bf16 v[0:15], v[126:129], v[122:125], v[0:15]
	ds_read_b128 v[114:117], v110 offset:32768
	ds_read_b128 v[118:121], v111 offset:49152
	ds_read_b128 v[122:125], v110 offset:36864
	ds_read_b128 v[126:129], v111 offset:53248
	s_waitcnt lgkmcnt(0)
	v_mfma_f32_32x32x16_bf16 v[48:63], v[118:121], v[114:117], v[48:63]
	v_mfma_f32_32x32x16_bf16 v[32:47], v[126:129], v[114:117], v[32:47]
	v_mfma_f32_32x32x16_bf16 v[16:31], v[118:121], v[122:125], v[16:31]
	v_mfma_f32_32x32x16_bf16 v[0:15], v[126:129], v[122:125], v[0:15]
	ds_read_b128 v[114:117], v112 offset:32768
	ds_read_b128 v[118:121], v113 offset:49152
	ds_read_b128 v[122:125], v112 offset:36864
	ds_read_b128 v[126:129], v113 offset:53248
	s_waitcnt vmcnt(0)
	s_waitcnt vmcnt(0) lgkmcnt(0)
	s_barrier
	v_mfma_f32_32x32x16_bf16 v[48:63], v[118:121], v[114:117], v[48:63]
	v_mfma_f32_32x32x16_bf16 v[32:47], v[126:129], v[114:117], v[32:47]
	global_load_lds_dwordx4 v64, s[98:99]
	s_mov_b32 m0, s83
	s_nop 0
	global_load_lds_dwordx4 v66, s[98:99]
	s_mov_b32 m0, s84
	v_mfma_f32_32x32x16_bf16 v[16:31], v[118:121], v[122:125], v[16:31]
	global_load_lds_dwordx4 v68, s[98:99]
	s_mov_b32 m0, s85
	s_nop 0
	global_load_lds_dwordx4 v70, s[98:99]
	s_mov_b32 m0, s86
	v_mfma_f32_32x32x16_bf16 v[0:15], v[126:129], v[122:125], v[0:15]
	global_load_lds_dwordx4 v64, s[100:101]
	s_mov_b32 m0, s87
	s_nop 0
	global_load_lds_dwordx4 v66, s[100:101]
	s_mov_b32 m0, s88
	s_nop 0
	global_load_lds_dwordx4 v68, s[100:101]
	s_mov_b32 m0, s89
	s_nop 0
	global_load_lds_dwordx4 v70, s[100:101]
	s_add_u32 s98, s98, 0x80
	s_addc_u32 s99, s99, 0
	s_add_u32 s100, s100, 0x80
	s_addc_u32 s101, s101, 0
	ds_read_b128 v[114:117], v106
	ds_read_b128 v[118:121], v107 offset:16384
	ds_read_b128 v[122:125], v106 offset:4096
	ds_read_b128 v[126:129], v107 offset:20480
	s_waitcnt lgkmcnt(0)
	v_mfma_f32_32x32x16_bf16 v[48:63], v[118:121], v[114:117], v[48:63]
	s_mov_b32 m0, s28
	v_mfma_f32_32x32x16_bf16 v[32:47], v[126:129], v[114:117], v[32:47]
	v_mfma_f32_32x32x16_bf16 v[16:31], v[118:121], v[122:125], v[16:31]
	v_mfma_f32_32x32x16_bf16 v[0:15], v[126:129], v[122:125], v[0:15]
	ds_read_b128 v[114:117], v108
	ds_read_b128 v[118:121], v109 offset:16384
	ds_read_b128 v[122:125], v108 offset:4096
	ds_read_b128 v[126:129], v109 offset:20480
	s_waitcnt lgkmcnt(0)
	v_mfma_f32_32x32x16_bf16 v[48:63], v[118:121], v[114:117], v[48:63]
	v_mfma_f32_32x32x16_bf16 v[32:47], v[126:129], v[114:117], v[32:47]
	v_mfma_f32_32x32x16_bf16 v[16:31], v[118:121], v[122:125], v[16:31]
	v_mfma_f32_32x32x16_bf16 v[0:15], v[126:129], v[122:125], v[0:15]
	ds_read_b128 v[114:117], v110
	ds_read_b128 v[118:121], v111 offset:16384
	ds_read_b128 v[122:125], v110 offset:4096
	ds_read_b128 v[126:129], v111 offset:20480
	s_waitcnt lgkmcnt(0)
	v_mfma_f32_32x32x16_bf16 v[48:63], v[118:121], v[114:117], v[48:63]
	v_mfma_f32_32x32x16_bf16 v[32:47], v[126:129], v[114:117], v[32:47]
	v_mfma_f32_32x32x16_bf16 v[16:31], v[118:121], v[122:125], v[16:31]
	v_mfma_f32_32x32x16_bf16 v[0:15], v[126:129], v[122:125], v[0:15]
	ds_read_b128 v[114:117], v112
	ds_read_b128 v[118:121], v113 offset:16384
	ds_read_b128 v[122:125], v112 offset:4096
	ds_read_b128 v[126:129], v113 offset:20480
	s_waitcnt vmcnt(0)
	s_waitcnt vmcnt(0) lgkmcnt(0)
	s_barrier
	v_mfma_f32_32x32x16_bf16 v[48:63], v[118:121], v[114:117], v[48:63]
	v_mfma_f32_32x32x16_bf16 v[32:47], v[126:129], v[114:117], v[32:47]
	global_load_lds_dwordx4 v64, s[98:99]
	s_mov_b32 m0, s29
	s_nop 0
	global_load_lds_dwordx4 v66, s[98:99]
	s_mov_b32 m0, s34
	v_mfma_f32_32x32x16_bf16 v[16:31], v[118:121], v[122:125], v[16:31]
	global_load_lds_dwordx4 v68, s[98:99]
	s_mov_b32 m0, s35
	s_nop 0
	global_load_lds_dwordx4 v70, s[98:99]
	s_mov_b32 m0, s70
	v_mfma_f32_32x32x16_bf16 v[0:15], v[126:129], v[122:125], v[0:15]
	global_load_lds_dwordx4 v64, s[100:101]
	s_mov_b32 m0, s71
	s_nop 0
	global_load_lds_dwordx4 v66, s[100:101]
	s_mov_b32 m0, s72
	s_nop 0
	global_load_lds_dwordx4 v68, s[100:101]
	s_mov_b32 m0, s73
	s_nop 0
	global_load_lds_dwordx4 v70, s[100:101]
	s_add_u32 s98, s98, 0x80
	s_addc_u32 s99, s99, 0
	s_add_u32 s100, s100, 0x80
	s_addc_u32 s101, s101, 0
	ds_read_b128 v[114:117], v106 offset:32768
	ds_read_b128 v[118:121], v107 offset:49152
	ds_read_b128 v[122:125], v106 offset:36864
	ds_read_b128 v[126:129], v107 offset:53248
	s_waitcnt lgkmcnt(0)
	v_mfma_f32_32x32x16_bf16 v[48:63], v[118:121], v[114:117], v[48:63]
	s_mov_b32 m0, s81
	v_mfma_f32_32x32x16_bf16 v[32:47], v[126:129], v[114:117], v[32:47]
	v_mfma_f32_32x32x16_bf16 v[16:31], v[118:121], v[122:125], v[16:31]
	v_mfma_f32_32x32x16_bf16 v[0:15], v[126:129], v[122:125], v[0:15]
	ds_read_b128 v[114:117], v108 offset:32768
	ds_read_b128 v[118:121], v109 offset:49152
	ds_read_b128 v[122:125], v108 offset:36864
	ds_read_b128 v[126:129], v109 offset:53248
	s_waitcnt lgkmcnt(0)
	v_mfma_f32_32x32x16_bf16 v[48:63], v[118:121], v[114:117], v[48:63]
	v_mfma_f32_32x32x16_bf16 v[32:47], v[126:129], v[114:117], v[32:47]
	v_mfma_f32_32x32x16_bf16 v[16:31], v[118:121], v[122:125], v[16:31]
	v_mfma_f32_32x32x16_bf16 v[0:15], v[126:129], v[122:125], v[0:15]
	ds_read_b128 v[114:117], v110 offset:32768
	ds_read_b128 v[118:121], v111 offset:49152
	ds_read_b128 v[122:125], v110 offset:36864
	ds_read_b128 v[126:129], v111 offset:53248
	s_waitcnt lgkmcnt(0)
	v_mfma_f32_32x32x16_bf16 v[48:63], v[118:121], v[114:117], v[48:63]
	v_mfma_f32_32x32x16_bf16 v[32:47], v[126:129], v[114:117], v[32:47]
	v_mfma_f32_32x32x16_bf16 v[16:31], v[118:121], v[122:125], v[16:31]
	v_mfma_f32_32x32x16_bf16 v[0:15], v[126:129], v[122:125], v[0:15]
	ds_read_b128 v[114:117], v112 offset:32768
	ds_read_b128 v[118:121], v113 offset:49152
	ds_read_b128 v[122:125], v112 offset:36864
	ds_read_b128 v[126:129], v113 offset:53248
	s_waitcnt vmcnt(0)
	s_waitcnt vmcnt(0) lgkmcnt(0)
	s_barrier
	v_mfma_f32_32x32x16_bf16 v[48:63], v[118:121], v[114:117], v[48:63]
	v_mfma_f32_32x32x16_bf16 v[32:47], v[126:129], v[114:117], v[32:47]
	global_load_lds_dwordx4 v64, s[98:99]
	s_mov_b32 m0, s83
	s_nop 0
	global_load_lds_dwordx4 v66, s[98:99]
	s_mov_b32 m0, s84
	v_mfma_f32_32x32x16_bf16 v[16:31], v[118:121], v[122:125], v[16:31]
	global_load_lds_dwordx4 v68, s[98:99]
	s_mov_b32 m0, s85
	s_nop 0
	global_load_lds_dwordx4 v70, s[98:99]
	s_mov_b32 m0, s86
	v_mfma_f32_32x32x16_bf16 v[0:15], v[126:129], v[122:125], v[0:15]
	global_load_lds_dwordx4 v64, s[100:101]
	s_mov_b32 m0, s87
	s_nop 0
	global_load_lds_dwordx4 v66, s[100:101]
	s_mov_b32 m0, s88
	s_nop 0
	global_load_lds_dwordx4 v68, s[100:101]
	s_mov_b32 m0, s89
	s_nop 0
	global_load_lds_dwordx4 v70, s[100:101]
	s_add_u32 s98, s98, 0x80
	s_addc_u32 s99, s99, 0
	s_add_u32 s100, s100, 0x80
	s_addc_u32 s101, s101, 0
	ds_read_b128 v[114:117], v106
	ds_read_b128 v[118:121], v107 offset:16384
	ds_read_b128 v[122:125], v106 offset:4096
	ds_read_b128 v[126:129], v107 offset:20480
	s_waitcnt lgkmcnt(0)
	v_mfma_f32_32x32x16_bf16 v[48:63], v[118:121], v[114:117], v[48:63]
	s_mov_b32 m0, s28
	v_mfma_f32_32x32x16_bf16 v[32:47], v[126:129], v[114:117], v[32:47]
	v_mfma_f32_32x32x16_bf16 v[16:31], v[118:121], v[122:125], v[16:31]
	v_mfma_f32_32x32x16_bf16 v[0:15], v[126:129], v[122:125], v[0:15]
	ds_read_b128 v[114:117], v108
	ds_read_b128 v[118:121], v109 offset:16384
	ds_read_b128 v[122:125], v108 offset:4096
	ds_read_b128 v[126:129], v109 offset:20480
	s_waitcnt lgkmcnt(0)
	v_mfma_f32_32x32x16_bf16 v[48:63], v[118:121], v[114:117], v[48:63]
	v_mfma_f32_32x32x16_bf16 v[32:47], v[126:129], v[114:117], v[32:47]
	v_mfma_f32_32x32x16_bf16 v[16:31], v[118:121], v[122:125], v[16:31]
	v_mfma_f32_32x32x16_bf16 v[0:15], v[126:129], v[122:125], v[0:15]
	ds_read_b128 v[114:117], v110
	ds_read_b128 v[118:121], v111 offset:16384
	ds_read_b128 v[122:125], v110 offset:4096
	ds_read_b128 v[126:129], v111 offset:20480
	s_waitcnt lgkmcnt(0)
	v_mfma_f32_32x32x16_bf16 v[48:63], v[118:121], v[114:117], v[48:63]
	v_mfma_f32_32x32x16_bf16 v[32:47], v[126:129], v[114:117], v[32:47]
	v_mfma_f32_32x32x16_bf16 v[16:31], v[118:121], v[122:125], v[16:31]
	v_mfma_f32_32x32x16_bf16 v[0:15], v[126:129], v[122:125], v[0:15]
	ds_read_b128 v[114:117], v112
	ds_read_b128 v[118:121], v113 offset:16384
	ds_read_b128 v[122:125], v112 offset:4096
	ds_read_b128 v[126:129], v113 offset:20480
	s_waitcnt vmcnt(0)
	s_waitcnt vmcnt(0) lgkmcnt(0)
	s_barrier
	v_mfma_f32_32x32x16_bf16 v[48:63], v[118:121], v[114:117], v[48:63]
	v_mfma_f32_32x32x16_bf16 v[32:47], v[126:129], v[114:117], v[32:47]
	global_load_lds_dwordx4 v64, s[98:99]
	s_mov_b32 m0, s29
	s_nop 0
	global_load_lds_dwordx4 v66, s[98:99]
	s_mov_b32 m0, s34
	v_mfma_f32_32x32x16_bf16 v[16:31], v[118:121], v[122:125], v[16:31]
	global_load_lds_dwordx4 v68, s[98:99]
	s_mov_b32 m0, s35
	s_nop 0
	global_load_lds_dwordx4 v70, s[98:99]
	s_mov_b32 m0, s70
	v_mfma_f32_32x32x16_bf16 v[0:15], v[126:129], v[122:125], v[0:15]
	global_load_lds_dwordx4 v64, s[100:101]
	s_mov_b32 m0, s71
	s_nop 0
	global_load_lds_dwordx4 v66, s[100:101]
	s_mov_b32 m0, s72
	s_nop 0
	global_load_lds_dwordx4 v68, s[100:101]
	s_mov_b32 m0, s73
	s_nop 0
	global_load_lds_dwordx4 v70, s[100:101]
	s_add_u32 s98, s98, 0x80
	s_addc_u32 s99, s99, 0
	s_add_u32 s100, s100, 0x80
	s_addc_u32 s101, s101, 0
	ds_read_b128 v[114:117], v106 offset:32768
	ds_read_b128 v[118:121], v107 offset:49152
	ds_read_b128 v[122:125], v106 offset:36864
	ds_read_b128 v[126:129], v107 offset:53248
	s_waitcnt lgkmcnt(0)
	v_mfma_f32_32x32x16_bf16 v[16:31], v[118:121], v[122:125], v[16:31]
	s_mov_b32 m0, s81
	v_mfma_f32_32x32x16_bf16 v[0:15], v[126:129], v[122:125], v[0:15]
	v_mfma_f32_32x32x16_bf16 v[32:47], v[126:129], v[114:117], v[32:47]
	v_mfma_f32_32x32x16_bf16 v[48:63], v[118:121], v[114:117], v[48:63]
	ds_read_b128 v[114:117], v108 offset:32768
	ds_read_b128 v[118:121], v109 offset:49152
	ds_read_b128 v[122:125], v108 offset:36864
	ds_read_b128 v[126:129], v109 offset:53248
	s_waitcnt lgkmcnt(0)
	v_mfma_f32_32x32x16_bf16 v[16:31], v[118:121], v[122:125], v[16:31]
	v_mfma_f32_32x32x16_bf16 v[0:15], v[126:129], v[122:125], v[0:15]
	v_mfma_f32_32x32x16_bf16 v[32:47], v[126:129], v[114:117], v[32:47]
	v_mfma_f32_32x32x16_bf16 v[48:63], v[118:121], v[114:117], v[48:63]
	ds_read_b128 v[114:117], v110 offset:32768
	ds_read_b128 v[118:121], v111 offset:49152
	ds_read_b128 v[122:125], v110 offset:36864
	ds_read_b128 v[126:129], v111 offset:53248
	s_waitcnt lgkmcnt(0)
	v_mfma_f32_32x32x16_bf16 v[16:31], v[118:121], v[122:125], v[16:31]
	v_mfma_f32_32x32x16_bf16 v[0:15], v[126:129], v[122:125], v[0:15]
	v_mfma_f32_32x32x16_bf16 v[32:47], v[126:129], v[114:117], v[32:47]
	v_mfma_f32_32x32x16_bf16 v[48:63], v[118:121], v[114:117], v[48:63]
	ds_read_b128 v[114:117], v112 offset:32768
	ds_read_b128 v[118:121], v113 offset:49152
	ds_read_b128 v[122:125], v112 offset:36864
	ds_read_b128 v[126:129], v113 offset:53248
	s_waitcnt vmcnt(0)
	s_waitcnt vmcnt(0) lgkmcnt(0)
	s_barrier
	global_load_lds_dwordx4 v64, s[98:99]
	s_mov_b32 m0, s83
	v_mfma_f32_32x32x16_bf16 v[16:31], v[118:121], v[122:125], v[16:31]
	global_load_lds_dwordx4 v66, s[98:99]
	s_mov_b32 m0, s84
	s_nop 0
	global_load_lds_dwordx4 v68, s[98:99]
	s_mov_b32 m0, s85
	v_mfma_f32_32x32x16_bf16 v[0:15], v[126:129], v[122:125], v[0:15]
	global_load_lds_dwordx4 v70, s[98:99]
	s_mov_b32 m0, s86
	s_nop 0
	global_load_lds_dwordx4 v64, s[100:101]
	s_mov_b32 m0, s87
	v_mfma_f32_32x32x16_bf16 v[32:47], v[126:129], v[114:117], v[32:47]
	global_load_lds_dwordx4 v66, s[100:101]
	s_mov_b32 m0, s88
	s_nop 0
	global_load_lds_dwordx4 v68, s[100:101]
	s_mov_b32 m0, s89
	v_mfma_f32_32x32x16_bf16 v[48:63], v[118:121], v[114:117], v[48:63]
	global_load_lds_dwordx4 v70, s[100:101]
	ds_read_b128 v[72:75], v106
	ds_read_b128 v[76:79], v107 offset:16384
	ds_read_b128 v[80:83], v106 offset:4096
	ds_read_b128 v[84:87], v107 offset:20480
	s_waitcnt lgkmcnt(0)
	v_mfma_f32_32x32x16_bf16 v[16:31], v[76:79], v[80:83], v[16:31]
	v_mfma_f32_32x32x16_bf16 v[0:15], v[84:87], v[80:83], v[0:15]
	v_mfma_f32_32x32x16_bf16 v[32:47], v[84:87], v[72:75], v[32:47]
	v_mfma_f32_32x32x16_bf16 v[48:63], v[76:79], v[72:75], v[48:63]
	ds_read_b128 v[72:75], v108
	ds_read_b128 v[76:79], v109 offset:16384
	ds_read_b128 v[80:83], v108 offset:4096
	ds_read_b128 v[84:87], v109 offset:20480
	s_waitcnt lgkmcnt(0)
	v_mfma_f32_32x32x16_bf16 v[16:31], v[76:79], v[80:83], v[16:31]
	v_mfma_f32_32x32x16_bf16 v[0:15], v[84:87], v[80:83], v[0:15]
	v_mfma_f32_32x32x16_bf16 v[32:47], v[84:87], v[72:75], v[32:47]
	v_mfma_f32_32x32x16_bf16 v[48:63], v[76:79], v[72:75], v[48:63]
	ds_read_b128 v[72:75], v110
	ds_read_b128 v[76:79], v111 offset:16384
	ds_read_b128 v[80:83], v110 offset:4096
	ds_read_b128 v[84:87], v111 offset:20480
	s_waitcnt lgkmcnt(0)
	v_mfma_f32_32x32x16_bf16 v[16:31], v[76:79], v[80:83], v[16:31]
	v_mfma_f32_32x32x16_bf16 v[0:15], v[84:87], v[80:83], v[0:15]
	v_mfma_f32_32x32x16_bf16 v[32:47], v[84:87], v[72:75], v[32:47]
	v_mfma_f32_32x32x16_bf16 v[48:63], v[76:79], v[72:75], v[48:63]
	ds_read_b128 v[72:75], v112
	ds_read_b128 v[76:79], v113 offset:16384
	ds_read_b128 v[80:83], v112 offset:4096
	ds_read_b128 v[84:87], v113 offset:20480
	s_waitcnt vmcnt(0)
	s_waitcnt vmcnt(0) lgkmcnt(0)
	s_barrier
	v_mfma_f32_32x32x16_bf16 v[16:31], v[76:79], v[80:83], v[16:31]
	v_mfma_f32_32x32x16_bf16 v[0:15], v[84:87], v[80:83], v[0:15]
	v_mfma_f32_32x32x16_bf16 v[32:47], v[84:87], v[72:75], v[32:47]
	v_mfma_f32_32x32x16_bf16 v[48:63], v[76:79], v[72:75], v[48:63]
	ds_read_b128 v[72:75], v113 offset:53248
	ds_read_b128 v[76:79], v112 offset:36864
	ds_read_b128 v[80:83], v113 offset:49152
	ds_read_b128 v[84:87], v112 offset:32768
	ds_read_b128 v[114:117], v111 offset:53248
	ds_read_b128 v[118:121], v110 offset:36864
	ds_read_b128 v[122:125], v111 offset:49152
	ds_read_b128 v[126:129], v110 offset:32768
	ds_read_b128 v[130:133], v109 offset:53248
	ds_read_b128 v[134:137], v108 offset:36864
	ds_read_b128 v[138:141], v109 offset:49152
	ds_read_b128 v[142:145], v108 offset:32768
	ds_read_b128 v[146:149], v107 offset:53248
	ds_read_b128 v[150:153], v106 offset:36864
	ds_read_b128 v[156:159], v107 offset:49152
	ds_read_b128 v[160:163], v106 offset:32768
	s_waitcnt vmcnt(0)
	s_waitcnt lgkmcnt(0)
	s_barrier
	v_mfma_f32_32x32x16_bf16 v[16:31], v[156:159], v[150:153], v[16:31]
	v_mfma_f32_32x32x16_bf16 v[0:15], v[146:149], v[150:153], v[0:15]
	v_mfma_f32_32x32x16_bf16 v[32:47], v[146:149], v[160:163], v[32:47]
	v_mfma_f32_32x32x16_bf16 v[48:63], v[156:159], v[160:163], v[48:63]
	v_mfma_f32_32x32x16_bf16 v[16:31], v[138:141], v[134:137], v[16:31]
	v_mfma_f32_32x32x16_bf16 v[0:15], v[130:133], v[134:137], v[0:15]
	v_mfma_f32_32x32x16_bf16 v[32:47], v[130:133], v[142:145], v[32:47]
	v_mfma_f32_32x32x16_bf16 v[48:63], v[138:141], v[142:145], v[48:63]
	v_mfma_f32_32x32x16_bf16 v[16:31], v[122:125], v[118:121], v[16:31]
	v_mfma_f32_32x32x16_bf16 v[0:15], v[114:117], v[118:121], v[0:15]
	v_mfma_f32_32x32x16_bf16 v[32:47], v[114:117], v[126:129], v[32:47]
	v_mfma_f32_32x32x16_bf16 v[48:63], v[122:125], v[126:129], v[48:63]
	v_mfma_f32_32x32x16_bf16 v[16:31], v[80:83], v[76:79], v[16:31]
	v_mfma_f32_32x32x16_bf16 v[0:15], v[72:75], v[76:79], v[0:15]
	v_add_u32_e32 v76, s80, v89
	v_ashrrev_i32_e32 v77, 31, v76
	v_mfma_f32_32x32x16_bf16 v[32:47], v[72:75], v[84:87], v[32:47]
	v_or_b32_e32 v72, s82, v90
	v_lshlrev_b64 v[74:75], 12, v[76:77]
	v_ashrrev_i32_e32 v73, 31, v72
	v_lshl_add_u64 v[78:79], s[40:41], 0, v[74:75]
	v_mfma_f32_32x32x16_bf16 v[48:63], v[80:83], v[84:87], v[48:63]
	v_lshlrev_b64 v[82:83], 2, v[72:73]
	v_lshl_add_u64 v[78:79], v[78:79], 0, v[82:83]
	v_lshl_add_u64 v[80:81], s[38:39], 0, v[74:75]
	v_lshl_add_u64 v[228:229], v[80:81], 0, v[82:83]
	v_or_b32_e32 v234, 32, v76
	v_ashrrev_i32_e32 v235, 31, v234
	v_lshlrev_b64 v[234:235], 12, v[234:235]
	v_lshl_add_u64 v[230:231], s[40:41], 0, v[234:235]
	v_lshl_add_u64 v[230:231], v[230:231], 0, v[82:83]
	v_lshl_add_u64 v[232:233], s[38:39], 0, v[234:235]
	v_lshl_add_u64 v[232:233], v[232:233], 0, v[82:83]
	s_waitcnt vmcnt(15)
	v_pk_fma_f32 v[166:167], v[166:167], s[78:79], v[50:51] op_sel_hi:[1,0,1]
	v_pk_fma_f32 v[164:165], v[164:165], s[78:79], v[48:49] op_sel_hi:[1,0,1]
	global_store_dwordx4 v[228:229], v[164:167], off
	s_waitcnt vmcnt(15)
	v_pk_fma_f32 v[168:169], v[168:169], s[78:79], v[52:53] op_sel_hi:[1,0,1]
	v_pk_fma_f32 v[170:171], v[170:171], s[78:79], v[54:55] op_sel_hi:[1,0,1]
	global_store_dwordx4 v[228:229], v[168:171], off offset:32
	s_waitcnt vmcnt(15)
	v_pk_fma_f32 v[172:173], v[172:173], s[78:79], v[56:57] op_sel_hi:[1,0,1]
	v_pk_fma_f32 v[174:175], v[174:175], s[78:79], v[58:59] op_sel_hi:[1,0,1]
	global_store_dwordx4 v[228:229], v[172:175], off offset:64
	s_waitcnt vmcnt(15)
	v_pk_fma_f32 v[176:177], v[176:177], s[78:79], v[60:61] op_sel_hi:[1,0,1]
	v_pk_fma_f32 v[178:179], v[178:179], s[78:79], v[62:63] op_sel_hi:[1,0,1]
	global_store_dwordx4 v[228:229], v[176:179], off offset:96
	s_waitcnt vmcnt(15)
	v_pk_fma_f32 v[182:183], v[182:183], s[78:79], v[34:35] op_sel_hi:[1,0,1]
	v_pk_fma_f32 v[180:181], v[180:181], s[78:79], v[32:33] op_sel_hi:[1,0,1]
	global_store_dwordx4 v[228:229], v[180:183], off offset:128
	s_waitcnt vmcnt(15)
	v_pk_fma_f32 v[184:185], v[184:185], s[78:79], v[36:37] op_sel_hi:[1,0,1]
	v_pk_fma_f32 v[186:187], v[186:187], s[78:79], v[38:39] op_sel_hi:[1,0,1]
	global_store_dwordx4 v[228:229], v[184:187], off offset:160
	s_waitcnt vmcnt(15)
	v_pk_fma_f32 v[188:189], v[188:189], s[78:79], v[40:41] op_sel_hi:[1,0,1]
	v_pk_fma_f32 v[190:191], v[190:191], s[78:79], v[42:43] op_sel_hi:[1,0,1]
	global_store_dwordx4 v[228:229], v[188:191], off offset:192
	s_waitcnt vmcnt(15)
	v_pk_fma_f32 v[192:193], v[192:193], s[78:79], v[44:45] op_sel_hi:[1,0,1]
	v_pk_fma_f32 v[194:195], v[194:195], s[78:79], v[46:47] op_sel_hi:[1,0,1]
	global_store_dwordx4 v[228:229], v[192:195], off offset:224
	s_waitcnt vmcnt(15)
	v_pk_fma_f32 v[198:199], v[198:199], s[78:79], v[18:19] op_sel_hi:[1,0,1]
	v_pk_fma_f32 v[196:197], v[196:197], s[78:79], v[16:17] op_sel_hi:[1,0,1]
	global_store_dwordx4 v[232:233], v[196:199], off
	s_waitcnt vmcnt(15)
	v_pk_fma_f32 v[200:201], v[200:201], s[78:79], v[20:21] op_sel_hi:[1,0,1]
	v_pk_fma_f32 v[202:203], v[202:203], s[78:79], v[22:23] op_sel_hi:[1,0,1]
	global_store_dwordx4 v[232:233], v[200:203], off offset:32
	s_waitcnt vmcnt(15)
	v_pk_fma_f32 v[204:205], v[204:205], s[78:79], v[24:25] op_sel_hi:[1,0,1]
	v_pk_fma_f32 v[206:207], v[206:207], s[78:79], v[26:27] op_sel_hi:[1,0,1]
	global_store_dwordx4 v[232:233], v[204:207], off offset:64
	s_waitcnt vmcnt(15)
	v_pk_fma_f32 v[208:209], v[208:209], s[78:79], v[28:29] op_sel_hi:[1,0,1]
	v_pk_fma_f32 v[210:211], v[210:211], s[78:79], v[30:31] op_sel_hi:[1,0,1]
	global_store_dwordx4 v[232:233], v[208:211], off offset:96
	s_waitcnt vmcnt(15)
	v_pk_fma_f32 v[214:215], v[214:215], s[78:79], v[2:3] op_sel_hi:[1,0,1]
	v_pk_fma_f32 v[212:213], v[212:213], s[78:79], v[0:1] op_sel_hi:[1,0,1]
	global_store_dwordx4 v[232:233], v[212:215], off offset:128
	s_waitcnt vmcnt(15)
	v_pk_fma_f32 v[216:217], v[216:217], s[78:79], v[4:5] op_sel_hi:[1,0,1]
	v_pk_fma_f32 v[218:219], v[218:219], s[78:79], v[6:7] op_sel_hi:[1,0,1]
	global_store_dwordx4 v[232:233], v[216:219], off offset:160
	s_waitcnt vmcnt(15)
	v_pk_fma_f32 v[220:221], v[220:221], s[78:79], v[8:9] op_sel_hi:[1,0,1]
	v_pk_fma_f32 v[222:223], v[222:223], s[78:79], v[10:11] op_sel_hi:[1,0,1]
	global_store_dwordx4 v[232:233], v[220:223], off offset:192
	s_waitcnt vmcnt(15)
	v_pk_fma_f32 v[224:225], v[224:225], s[78:79], v[12:13] op_sel_hi:[1,0,1]
	v_pk_fma_f32 v[226:227], v[226:227], s[78:79], v[14:15] op_sel_hi:[1,0,1]
	global_store_dwordx4 v[232:233], v[224:227], off offset:224
	s_add_i32 s79, s79, s33
	s_add_i32 s28, s2, s79
	s_cmpk_lt_i32 s28, 0x400
	s_cbranch_scc0 .LBB0_564
